# W_ING/W_BR/W_O weight conversion moved from the M2b sub-phase into the idle workgroups of the last half-empty G3a GEMM round
# speedup vs baseline: 1.0129x; 1.0013x over previous
.LBB0_434:
	s_waitcnt vmcnt(0)
	s_barrier
	s_cmpk_lt_i32 s90, 0x80
	s_cbranch_scc1 .Lcv0_skip
	s_mov_b64 s[44:45], s[88:89]
	s_load_dwordx2 s[46:47], s[88:89], 0x150
	s_sub_i32 s61, s90, 64
	s_movk_i32 s62, 0xc0
	s_lshr_b32 s63, s91, 6
	v_mbcnt_hi_u32_b32 v66, -1, v210
	v_lshlrev_b32_e32 v8, 2, v66
	s_waitcnt lgkmcnt(0)
	v_lshrrev_b32_e32 v9, 3, v66
	s_movk_i32 s4, 0x84
	v_mov_b32_e32 v0, 0x420
	v_mad_u32_u24 v20, v9, s4, v0
	v_mov_b32_e32 v0, 0x840
	v_mad_u32_u24 v31, v9, s4, v0
	v_lshlrev_b32_e32 v0, 3, v66
	v_and_b32_e32 v0, 56, v0
	s_load_dwordx2 s[12:13], s[44:45], 0x28
	s_load_dwordx2 s[14:15], s[44:45], 0x120
	v_mov_b32_e32 v1, 0
	v_mul_u32_u24_e32 v4, 0x84, v0
	v_lshlrev_b32_e32 v0, 1, v0
	s_lshl_b32 s2, s63, 14
	v_lshl_add_u64 v[14:15], s[46:47], 0, v[0:1]
	s_mov_b64 s[4:5], 0x400000
	s_add_i32 s6, s2, 0
	s_lshl_b32 s2, s61, 3
	v_lshl_add_u64 v[2:3], v[14:15], 0, s[4:5]
	v_lshlrev_b32_e32 v0, 2, v9
	s_mov_b64 s[4:5], 0xe00000
	s_add_i32 s2, s2, s63
	s_lshl_b32 s7, s62, 3
	v_add3_u32 v27, s6, v4, v0
	v_lshl_add_u64 v[4:5], v[14:15], 0, s[4:5]
	s_mov_b64 s[4:5], 0xc00000
	s_addk_i32 s2, 0xfe00
	s_add_i32 s3, s7, 0xfffffe00
	v_lshl_add_u64 v[6:7], v[14:15], 0, s[4:5]
	s_mov_b64 s[4:5], 0x1000000
	s_waitcnt lgkmcnt(0)
	s_cmp_lg_u64 s[12:13], 0
	v_lshl_add_u64 v[10:11], v[14:15], 0, s[4:5]
	s_mov_b64 s[4:5], 0x1b00000
	s_cselect_b64 s[16:17], -1, 0
	s_cmp_lg_u64 s[14:15], 0
	v_lshl_add_u64 v[12:13], v[14:15], 0, s[4:5]
	s_mov_b64 s[4:5], 0x2080000
	s_cselect_b64 s[18:19], -1, 0
	v_and_b32_e32 v16, 28, v8
	v_lshl_add_u64 v[14:15], v[14:15], 0, s[4:5]
	s_lshl_b32 s4, s61, 4
	s_lshl_b32 s5, s63, 1
	v_lshl_add_u32 v17, v16, 2, s6
	v_mul_u32_u24_e32 v18, 0x84, v9
	s_add_i32 s4, s4, s5
	s_lshl_b32 s23, s62, 4
	s_lshl_b32 s25, s62, 6
	v_cndmask_b32_e64 v0, 0, 1, s[16:17]
	s_mov_b32 s11, 0
	v_or_b32_e32 v19, 8, v9
	v_or_b32_e32 v21, 16, v9
	v_or_b32_e32 v22, 24, v9
	v_or_b32_e32 v23, 32, v9
	v_or_b32_e32 v24, 40, v9
	v_or_b32_e32 v25, 48, v9
	v_or_b32_e32 v26, 56, v9
	v_bitop3_b32 v28, v9, 15, 24 bitop3:0xc8
	s_add_i32 s22, s4, 0x1ec00
	s_addk_i32 s23, 0xfc00
	s_lshl_b32 s24, s2, 3
	s_addk_i32 s25, 0xf000
	s_sub_i32 s26, 0, s7
	v_cmp_ne_u32_e64 s[4:5], 1, v0
	s_mov_b64 s[20:21], 0x2000
	s_movk_i32 s27, 0x6000
	v_add_u32_e32 v29, v17, v18
	v_add_u32_e32 v30, v17, v20
	s_mov_b32 s28, 0x80000
	s_movk_i32 s29, 0x2c00
	s_mov_b32 s30, 0x40000
	v_lshlrev_b32_e32 v0, 2, v16
	v_add_u32_e32 v31, v17, v31
	s_branch .Lcv0_869

.Lcv0_869:
	s_cmpk_gt_i32 s2, 0xbff
	s_cbranch_scc1 .Lcv0_937
	s_cmpk_gt_u32 s2, 0x7ff
	s_cbranch_scc1 .Lcv0_884

	s_lshr_b32 s6, s2, 1
	s_and_b32 s10, s6, 0x3c0
	v_or_b32_e32 v32, s10, v9
	v_mov_b32_e32 v18, 1.0
	s_and_b64 vcc, exec, s[4:5]
	v_mov_b32_e32 v20, 1.0
	s_cbranch_vccnz .Lcv0_872

	v_lshlrev_b32_e32 v16, 2, v32
	global_load_dword v20, v16, s[12:13]
.Lcv0_872:
	s_load_dwordx2 s[6:7], s[44:45], 0x30
	s_lshl_b32 s31, s2, 5
	s_and_b32 s31, s31, 0xfe0
	s_lshl_b32 s33, s31, 2
	s_waitcnt lgkmcnt(0)
	s_add_u32 s6, s6, s33
	s_addc_u32 s7, s7, 0
	v_lshl_add_u64 v[16:17], s[6:7], 0, v[0:1]
	v_lshl_add_u64 v[16:17], v[16:17], 0, s[20:21]
	v_mad_u64_u32 v[32:33], s[6:7], v32, s27, v[16:17]
	global_load_dwordx4 v[32:35], v[32:33], off
	s_and_b64 vcc, exec, s[4:5]
	s_waitcnt vmcnt(0)
	v_pk_mul_f32 v[32:33], v[32:33], v[20:21] op_sel_hi:[1,0]
	v_pk_mul_f32 v[34:35], v[34:35], v[20:21] op_sel_hi:[1,0]
	ds_write2_b32 v29, v32, v33 offset1:1
	ds_write2_b32 v29, v34, v35 offset0:2 offset1:3
	v_add_lshl_u32 v32, s10, v9, 2
	s_cbranch_vccnz .Lcv0_874

	global_load_dword v18, v32, s[12:13] offset:32
.Lcv0_874:
	v_or_b32_e32 v20, s10, v19
	v_mad_u64_u32 v[34:35], s[6:7], v20, s27, v[16:17]
	global_load_dwordx4 v[34:37], v[34:35], off
	v_mov_b32_e32 v20, 1.0
	s_and_b64 vcc, exec, s[4:5]
	s_waitcnt vmcnt(0)
	v_pk_mul_f32 v[36:37], v[36:37], v[18:19] op_sel_hi:[1,0]
	v_pk_mul_f32 v[34:35], v[34:35], v[18:19] op_sel_hi:[1,0]
	v_mov_b32_e32 v18, 1.0
	ds_write2_b32 v30, v34, v35 offset1:1
	ds_write2_b32 v30, v36, v37 offset0:2 offset1:3
	s_cbranch_vccnz .Lcv0_876

	global_load_dword v18, v32, s[12:13] offset:64
.Lcv0_876:
	v_or_b32_e32 v33, s10, v21
	v_mad_u64_u32 v[34:35], s[6:7], v33, s27, v[16:17]
	global_load_dwordx4 v[34:37], v[34:35], off
	s_and_b64 vcc, exec, s[4:5]
	s_waitcnt vmcnt(0)
	v_pk_mul_f32 v[34:35], v[34:35], v[18:19] op_sel_hi:[1,0]
	v_pk_mul_f32 v[36:37], v[36:37], v[18:19] op_sel_hi:[1,0]
	ds_write2_b32 v31, v34, v35 offset1:1
	ds_write2_b32 v31, v36, v37 offset0:2 offset1:3
	s_cbranch_vccnz .Lcv0_878

	global_load_dword v20, v32, s[12:13] offset:96
.Lcv0_878:
	v_or_b32_e32 v18, s10, v22
	v_mad_u64_u32 v[34:35], s[6:7], v18, s27, v[16:17]
	global_load_dwordx4 v[34:37], v[34:35], off
	v_add_u32_e32 v33, 0x420, v31
	v_mov_b32_e32 v18, 1.0
	s_and_b64 vcc, exec, s[4:5]
	v_add_u32_e32 v40, 0x428, v31
	s_waitcnt vmcnt(0)
	v_pk_mul_f32 v[36:37], v[36:37], v[20:21] op_sel_hi:[1,0]
	v_pk_mul_f32 v[34:35], v[34:35], v[20:21] op_sel_hi:[1,0]
	v_mov_b32_e32 v20, 1.0
	ds_write2_b32 v33, v34, v35 offset1:1
	ds_write2_b32 v40, v36, v37 offset1:1
	s_cbranch_vccnz .Lcv0_880

	global_load_dword v20, v32, s[12:13] offset:128
.Lcv0_880:
	v_or_b32_e32 v33, s10, v23
	v_mad_u64_u32 v[34:35], s[6:7], v33, s27, v[16:17]
	global_load_dwordx4 v[34:37], v[34:35], off
	v_add_u32_e32 v33, 0x840, v31
	s_and_b64 vcc, exec, s[4:5]
	v_add_u32_e32 v40, 0x848, v31
	s_waitcnt vmcnt(0)
	v_pk_mul_f32 v[34:35], v[34:35], v[20:21] op_sel_hi:[1,0]
	v_pk_mul_f32 v[36:37], v[36:37], v[20:21] op_sel_hi:[1,0]
	ds_write2_b32 v33, v34, v35 offset1:1
	ds_write2_b32 v40, v36, v37 offset1:1
	s_cbranch_vccnz .Lcv0_882

	global_load_dword v18, v32, s[12:13] offset:160
.Lcv0_882:
	v_or_b32_e32 v20, s10, v24
	v_mad_u64_u32 v[34:35], s[6:7], v20, s27, v[16:17]
	global_load_dwordx4 v[34:37], v[34:35], off
	v_add_u32_e32 v20, 0xc60, v31
	s_and_b64 vcc, exec, s[4:5]
	v_add_u32_e32 v33, 0xc68, v31
	s_waitcnt vmcnt(0)
	v_pk_mul_f32 v[34:35], v[34:35], v[18:19] op_sel_hi:[1,0]
	v_pk_mul_f32 v[36:37], v[36:37], v[18:19] op_sel_hi:[1,0]
	ds_write2_b32 v20, v34, v35 offset1:1
	ds_write2_b32 v33, v36, v37 offset1:1
	s_cbranch_vccnz .Lcv0_888

	global_load_dword v18, v32, s[12:13] offset:192
	s_branch .Lcv0_889

.Lcv0_885:
	s_cmpk_eq_i32 s31, 0xa00
	s_cbranch_scc0 .Lcv0_887

	s_load_dwordx2 s[34:35], s[44:45], 0x118
	s_add_i32 s6, s22, 0xfffffc00
	s_and_b32 s7, s6, 0x1ffc0
	s_lshl_b32 s6, s2, 5
	s_and_b32 s6, s6, 0x3e0
	s_lshl_b32 s10, s6, 2
	s_waitcnt lgkmcnt(0)
	s_add_u32 s34, s34, s10
	v_or_b32_e32 v18, s7, v9
	s_addc_u32 s35, s35, 0
	v_lshlrev_b32_e32 v32, 12, v18
	v_or_b32_e32 v18, s7, v19
	v_lshl_add_u64 v[16:17], s[34:35], 0, v[0:1]
	v_mov_b32_e32 v33, v1
	v_lshlrev_b32_e32 v34, 12, v18
	v_mov_b32_e32 v35, v1
	v_lshl_add_u64 v[32:33], v[16:17], 0, v[32:33]
	v_lshl_add_u64 v[36:37], v[16:17], 0, v[34:35]
	v_or_b32_e32 v18, s7, v21
	global_load_dwordx4 v[32:35], v[32:33], off
	s_nop 0
	global_load_dwordx4 v[40:43], v[36:37], off
	v_lshlrev_b32_e32 v36, 12, v18
	v_or_b32_e32 v18, s7, v22
	v_mov_b32_e32 v37, v1
	v_lshlrev_b32_e32 v44, 12, v18
	v_mov_b32_e32 v45, v1
	v_lshl_add_u64 v[36:37], v[16:17], 0, v[36:37]
	v_lshl_add_u64 v[48:49], v[16:17], 0, v[44:45]
	v_or_b32_e32 v18, s7, v23
	global_load_dwordx4 v[44:47], v[36:37], off
	s_nop 0
	global_load_dwordx4 v[48:51], v[48:49], off
	v_lshlrev_b32_e32 v36, 12, v18
	v_or_b32_e32 v18, s7, v24
	v_mov_b32_e32 v37, v1
	v_lshlrev_b32_e32 v52, 12, v18
	v_mov_b32_e32 v53, v1
	v_lshl_add_u64 v[36:37], v[16:17], 0, v[36:37]
	v_lshl_add_u64 v[56:57], v[16:17], 0, v[52:53]
	global_load_dwordx4 v[52:55], v[36:37], off
	s_nop 0
	global_load_dwordx4 v[56:59], v[56:57], off
	v_or_b32_e32 v18, s7, v25
	v_lshlrev_b32_e32 v36, 12, v18
	v_mov_b32_e32 v37, v1
	v_lshl_add_u64 v[36:37], v[16:17], 0, v[36:37]
	v_or_b32_e32 v18, s7, v26
	global_load_dwordx4 v[60:63], v[36:37], off
	v_lshlrev_b32_e32 v36, 12, v18
	v_mov_b32_e32 v37, v1
	v_lshl_add_u64 v[16:17], v[16:17], 0, v[36:37]
	global_load_dwordx4 v[68:71], v[16:17], off
	v_add_u32_e32 v16, 0x420, v29
	v_add_u32_e32 v17, 0x428, v29
	v_add_u32_e32 v18, 0x840, v29
	v_add_u32_e32 v20, 0x848, v29
	v_add_u32_e32 v36, 0xc60, v29
	v_add_u32_e32 v37, 0xc68, v29
	v_add_u32_e32 v65, 0x1080, v29
	v_add_u32_e32 v72, 0x1088, v29
	v_add_u32_e32 v73, 0x14a0, v29
	v_add_u32_e32 v74, 0x14a8, v29
	v_add_u32_e32 v75, 0x18c0, v29
	v_add_u32_e32 v76, 0x18c8, v29
	v_add_u32_e32 v77, 0x1ce0, v29
	v_add_u32_e32 v78, 0x1ce8, v29
	s_lshl_b32 s10, s7, 1
	s_waitcnt vmcnt(7)
	ds_write2_b32 v29, v32, v33 offset1:1
	ds_write2_b32 v29, v34, v35 offset0:2 offset1:3
	s_waitcnt vmcnt(6)
	ds_write2_b32 v16, v40, v41 offset1:1
	ds_write2_b32 v17, v42, v43 offset1:1
	s_waitcnt vmcnt(5)
	ds_write2_b32 v18, v44, v45 offset1:1
	ds_write2_b32 v20, v46, v47 offset1:1
	s_waitcnt vmcnt(4)
	ds_write2_b32 v36, v48, v49 offset1:1
	ds_write2_b32 v37, v50, v51 offset1:1
	s_waitcnt vmcnt(3)
	ds_write2_b32 v65, v52, v53 offset1:1
	ds_write2_b32 v72, v54, v55 offset1:1
	s_waitcnt vmcnt(2)
	ds_write2_b32 v73, v56, v57 offset1:1
	ds_write2_b32 v74, v58, v59 offset1:1
	s_waitcnt vmcnt(1)
	ds_write2_b32 v75, v60, v61 offset1:1
	ds_write2_b32 v76, v62, v63 offset1:1
	s_waitcnt vmcnt(0)
	ds_write2_b32 v77, v68, v69 offset1:1
	ds_write2_b32 v78, v70, v71 offset1:1
	s_waitcnt lgkmcnt(0)
	ds_read2_b32 v[16:17], v27 offset1:33
	s_waitcnt lgkmcnt(0)
	v_cvt_pk_bf16_f32 v32, v16, v17
	ds_read2_b32 v[16:17], v27 offset0:66 offset1:99
	s_waitcnt lgkmcnt(0)
	v_cvt_pk_bf16_f32 v33, v16, v17
	ds_read2_b32 v[16:17], v27 offset0:132 offset1:165
	v_or_b32_e32 v18, s6, v9
	s_waitcnt lgkmcnt(0)
	v_cvt_pk_bf16_f32 v34, v16, v17
	ds_read2_b32 v[16:17], v27 offset0:198 offset1:231
	v_mov_b32_e32 v37, v1
	v_lshlrev_b32_e32 v36, 11, v18
	v_lshl_add_u64 v[40:41], v[4:5], 0, s[10:11]
	s_waitcnt lgkmcnt(0)
	v_cvt_pk_bf16_f32 v35, v16, v17
	ds_read2_b32 v[16:17], v27 offset0:8 offset1:41
	v_lshl_add_u64 v[36:37], v[40:41], 0, v[36:37]
	global_store_dwordx4 v[36:37], v[32:35], off
	v_or_b32_e32 v18, s6, v19
	v_mov_b32_e32 v37, v1
	s_waitcnt lgkmcnt(0)
	v_cvt_pk_bf16_f32 v32, v16, v17
	ds_read2_b32 v[16:17], v27 offset0:74 offset1:107
	s_waitcnt lgkmcnt(0)
	v_cvt_pk_bf16_f32 v33, v16, v17
	ds_read2_b32 v[16:17], v27 offset0:140 offset1:173
	s_waitcnt lgkmcnt(0)
	v_cvt_pk_bf16_f32 v34, v16, v17
	ds_read2_b32 v[16:17], v27 offset0:206 offset1:239
	v_lshlrev_b32_e32 v36, 11, v18
	s_waitcnt lgkmcnt(0)
	v_cvt_pk_bf16_f32 v35, v16, v17
	ds_read2_b32 v[16:17], v27 offset0:16 offset1:49
	v_lshl_add_u64 v[36:37], v[40:41], 0, v[36:37]
	global_store_dwordx4 v[36:37], v[32:35], off
	v_or_b32_e32 v18, s6, v21
	v_mov_b32_e32 v37, v1
	s_waitcnt lgkmcnt(0)
	v_cvt_pk_bf16_f32 v32, v16, v17
	ds_read2_b32 v[16:17], v27 offset0:82 offset1:115
	s_waitcnt lgkmcnt(0)
	v_cvt_pk_bf16_f32 v33, v16, v17
	ds_read2_b32 v[16:17], v27 offset0:148 offset1:181
	s_waitcnt lgkmcnt(0)
	v_cvt_pk_bf16_f32 v34, v16, v17
	ds_read2_b32 v[16:17], v27 offset0:214 offset1:247
	v_lshlrev_b32_e32 v36, 11, v18
	s_waitcnt lgkmcnt(0)
	v_cvt_pk_bf16_f32 v35, v16, v17
	ds_read2_b32 v[16:17], v27 offset0:24 offset1:57
	v_lshl_add_u64 v[36:37], v[40:41], 0, v[36:37]
	global_store_dwordx4 v[36:37], v[32:35], off
	v_or_b32_e32 v18, s6, v22
	v_mov_b32_e32 v37, v1
	s_waitcnt lgkmcnt(0)
	v_cvt_pk_bf16_f32 v32, v16, v17
	ds_read2_b32 v[16:17], v27 offset0:90 offset1:123
	s_waitcnt lgkmcnt(0)
	v_cvt_pk_bf16_f32 v33, v16, v17
	ds_read2_b32 v[16:17], v27 offset0:156 offset1:189
	s_waitcnt lgkmcnt(0)
	v_cvt_pk_bf16_f32 v34, v16, v17
	ds_read2_b32 v[16:17], v27 offset0:222 offset1:255
	v_lshlrev_b32_e32 v36, 11, v18
	s_waitcnt lgkmcnt(0)
	v_cvt_pk_bf16_f32 v35, v16, v17
	v_lshl_add_u64 v[16:17], v[40:41], 0, v[36:37]
	global_store_dwordx4 v[16:17], v[32:35], off
	s_waitcnt lgkmcnt(0)

.Lcv0_889:
	v_or_b32_e32 v20, s10, v25
	v_mad_u64_u32 v[34:35], s[6:7], v20, s27, v[16:17]
	global_load_dwordx4 v[34:37], v[34:35], off
	v_add_u32_e32 v20, 0x1080, v31
	s_and_b64 vcc, exec, s[16:17]
	v_add_u32_e32 v33, 0x1088, v31
	s_waitcnt vmcnt(0)
	v_pk_mul_f32 v[34:35], v[34:35], v[18:19] op_sel_hi:[1,0]
	v_pk_mul_f32 v[36:37], v[36:37], v[18:19] op_sel_hi:[1,0]
	ds_write2_b32 v20, v34, v35 offset1:1
	ds_write2_b32 v33, v36, v37 offset1:1
	s_cbranch_vccz .Lcv0_936

	global_load_dword v18, v32, s[12:13] offset:224
	s_cbranch_execnz .Lcv0_892

.Lcv0_894:
	s_cmpk_lg_i32 s31, 0x800
	s_cbranch_scc1 .Lcv0_896

	s_load_dwordx2 s[34:35], s[44:45], 0x110
	s_lshl_b32 s6, s2, 5
	s_and_b32 s6, s6, 0x3e0
	s_and_b32 s7, s22, 0x1ffc0
	s_lshl_b32 s10, s6, 2
	s_waitcnt lgkmcnt(0)
	s_add_u32 s34, s34, s10
	v_or_b32_e32 v18, s7, v9
	s_addc_u32 s35, s35, 0
	v_lshlrev_b32_e32 v32, 12, v18
	v_or_b32_e32 v18, s7, v19
	v_lshl_add_u64 v[16:17], s[34:35], 0, v[0:1]
	v_mov_b32_e32 v33, v1
	v_lshlrev_b32_e32 v34, 12, v18
	v_mov_b32_e32 v35, v1
	v_lshl_add_u64 v[32:33], v[16:17], 0, v[32:33]
	v_lshl_add_u64 v[36:37], v[16:17], 0, v[34:35]
	v_or_b32_e32 v18, s7, v21
	global_load_dwordx4 v[32:35], v[32:33], off
	s_nop 0
	global_load_dwordx4 v[40:43], v[36:37], off
	v_lshlrev_b32_e32 v36, 12, v18
	v_or_b32_e32 v18, s7, v22
	v_mov_b32_e32 v37, v1
	v_lshlrev_b32_e32 v44, 12, v18
	v_mov_b32_e32 v45, v1
	v_lshl_add_u64 v[36:37], v[16:17], 0, v[36:37]
	v_lshl_add_u64 v[48:49], v[16:17], 0, v[44:45]
	v_or_b32_e32 v18, s7, v23
	global_load_dwordx4 v[44:47], v[36:37], off
	s_nop 0
	global_load_dwordx4 v[48:51], v[48:49], off
	v_lshlrev_b32_e32 v36, 12, v18
	v_or_b32_e32 v18, s7, v24
	v_mov_b32_e32 v37, v1
	v_lshlrev_b32_e32 v52, 12, v18
	v_mov_b32_e32 v53, v1
	v_lshl_add_u64 v[36:37], v[16:17], 0, v[36:37]
	v_lshl_add_u64 v[56:57], v[16:17], 0, v[52:53]
	global_load_dwordx4 v[52:55], v[36:37], off
	s_nop 0
	global_load_dwordx4 v[56:59], v[56:57], off
	v_or_b32_e32 v18, s7, v25
	v_lshlrev_b32_e32 v36, 12, v18
	v_mov_b32_e32 v37, v1
	v_lshl_add_u64 v[36:37], v[16:17], 0, v[36:37]
	v_or_b32_e32 v18, s7, v26
	global_load_dwordx4 v[60:63], v[36:37], off
	v_lshlrev_b32_e32 v36, 12, v18
	v_mov_b32_e32 v37, v1
	v_lshl_add_u64 v[16:17], v[16:17], 0, v[36:37]
	global_load_dwordx4 v[68:71], v[16:17], off
	v_add_u32_e32 v16, 0x420, v29
	v_add_u32_e32 v17, 0x428, v29
	v_add_u32_e32 v18, 0x840, v29
	v_add_u32_e32 v20, 0x848, v29
	v_add_u32_e32 v36, 0xc60, v29
	v_add_u32_e32 v37, 0xc68, v29
	v_add_u32_e32 v65, 0x1080, v29
	v_add_u32_e32 v72, 0x1088, v29
	v_add_u32_e32 v73, 0x14a0, v29
	v_add_u32_e32 v74, 0x14a8, v29
	v_add_u32_e32 v75, 0x18c0, v29
	v_add_u32_e32 v76, 0x18c8, v29
	v_add_u32_e32 v77, 0x1ce0, v29
	v_add_u32_e32 v78, 0x1ce8, v29
	s_lshl_b32 s10, s7, 1
	s_waitcnt vmcnt(7)
	ds_write2_b32 v29, v32, v33 offset1:1
	ds_write2_b32 v29, v34, v35 offset0:2 offset1:3
	s_waitcnt vmcnt(6)
	ds_write2_b32 v16, v40, v41 offset1:1
	ds_write2_b32 v17, v42, v43 offset1:1
	s_waitcnt vmcnt(5)
	ds_write2_b32 v18, v44, v45 offset1:1
	ds_write2_b32 v20, v46, v47 offset1:1
	s_waitcnt vmcnt(4)
	ds_write2_b32 v36, v48, v49 offset1:1
	ds_write2_b32 v37, v50, v51 offset1:1
	s_waitcnt vmcnt(3)
	ds_write2_b32 v65, v52, v53 offset1:1
	ds_write2_b32 v72, v54, v55 offset1:1
	s_waitcnt vmcnt(2)
	ds_write2_b32 v73, v56, v57 offset1:1
	ds_write2_b32 v74, v58, v59 offset1:1
	s_waitcnt vmcnt(1)
	ds_write2_b32 v75, v60, v61 offset1:1
	ds_write2_b32 v76, v62, v63 offset1:1
	s_waitcnt vmcnt(0)
	ds_write2_b32 v77, v68, v69 offset1:1
	ds_write2_b32 v78, v70, v71 offset1:1
	s_waitcnt lgkmcnt(0)
	ds_read2_b32 v[16:17], v27 offset1:33
	s_waitcnt lgkmcnt(0)
	v_cvt_pk_bf16_f32 v32, v16, v17
	ds_read2_b32 v[16:17], v27 offset0:66 offset1:99
	s_waitcnt lgkmcnt(0)
	v_cvt_pk_bf16_f32 v33, v16, v17
	ds_read2_b32 v[16:17], v27 offset0:132 offset1:165
	v_or_b32_e32 v18, s6, v9
	s_waitcnt lgkmcnt(0)
	v_cvt_pk_bf16_f32 v34, v16, v17
	ds_read2_b32 v[16:17], v27 offset0:198 offset1:231
	v_mov_b32_e32 v37, v1
	v_lshlrev_b32_e32 v36, 11, v18
	v_lshl_add_u64 v[40:41], v[6:7], 0, s[10:11]
	s_waitcnt lgkmcnt(0)
	v_cvt_pk_bf16_f32 v35, v16, v17
	ds_read2_b32 v[16:17], v27 offset0:8 offset1:41
	v_lshl_add_u64 v[36:37], v[40:41], 0, v[36:37]
	global_store_dwordx4 v[36:37], v[32:35], off
	v_or_b32_e32 v18, s6, v19
	v_mov_b32_e32 v37, v1
	s_waitcnt lgkmcnt(0)
	v_cvt_pk_bf16_f32 v32, v16, v17
	ds_read2_b32 v[16:17], v27 offset0:74 offset1:107
	s_waitcnt lgkmcnt(0)
	v_cvt_pk_bf16_f32 v33, v16, v17
	ds_read2_b32 v[16:17], v27 offset0:140 offset1:173
	s_waitcnt lgkmcnt(0)
	v_cvt_pk_bf16_f32 v34, v16, v17
	ds_read2_b32 v[16:17], v27 offset0:206 offset1:239
	v_lshlrev_b32_e32 v36, 11, v18
	s_waitcnt lgkmcnt(0)
	v_cvt_pk_bf16_f32 v35, v16, v17
	ds_read2_b32 v[16:17], v27 offset0:16 offset1:49
	v_lshl_add_u64 v[36:37], v[40:41], 0, v[36:37]
	global_store_dwordx4 v[36:37], v[32:35], off
	v_or_b32_e32 v18, s6, v21
	v_mov_b32_e32 v37, v1
	s_waitcnt lgkmcnt(0)
	v_cvt_pk_bf16_f32 v32, v16, v17
	ds_read2_b32 v[16:17], v27 offset0:82 offset1:115
	s_waitcnt lgkmcnt(0)
	v_cvt_pk_bf16_f32 v33, v16, v17
	ds_read2_b32 v[16:17], v27 offset0:148 offset1:181
	s_waitcnt lgkmcnt(0)
	v_cvt_pk_bf16_f32 v34, v16, v17
	ds_read2_b32 v[16:17], v27 offset0:214 offset1:247
	v_lshlrev_b32_e32 v36, 11, v18
	s_waitcnt lgkmcnt(0)
	v_cvt_pk_bf16_f32 v35, v16, v17
	ds_read2_b32 v[16:17], v27 offset0:24 offset1:57
	v_lshl_add_u64 v[36:37], v[40:41], 0, v[36:37]
	global_store_dwordx4 v[36:37], v[32:35], off
	v_or_b32_e32 v18, s6, v22
	v_mov_b32_e32 v37, v1
	s_waitcnt lgkmcnt(0)
	v_cvt_pk_bf16_f32 v32, v16, v17
	ds_read2_b32 v[16:17], v27 offset0:90 offset1:123
	s_waitcnt lgkmcnt(0)
	v_cvt_pk_bf16_f32 v33, v16, v17
	ds_read2_b32 v[16:17], v27 offset0:156 offset1:189
	s_waitcnt lgkmcnt(0)
	v_cvt_pk_bf16_f32 v34, v16, v17
	ds_read2_b32 v[16:17], v27 offset0:222 offset1:255
	v_lshlrev_b32_e32 v36, 11, v18
	s_waitcnt lgkmcnt(0)
	v_cvt_pk_bf16_f32 v35, v16, v17
	v_lshl_add_u64 v[16:17], v[40:41], 0, v[36:37]
	global_store_dwordx4 v[16:17], v[32:35], off
	s_waitcnt lgkmcnt(0)
.Lcv0_896:
	s_add_i32 s31, s2, 0xfffff400
	v_cndmask_b32_e64 v16, 0, 1, s[18:19]
	s_cmpk_gt_u32 s31, 0x57f
	v_cmp_ne_u32_e64 s[6:7], 1, v16
	s_cbranch_scc1 .Lcv0_914

	s_and_b32 s33, s31, 0xffff
	s_mul_i32 s33, s33, 0xba2f
	s_lshr_b32 s10, s33, 16
	s_and_b32 s10, s10, 0xffc0
	v_or_b32_e32 v32, s10, v9
	v_mov_b32_e32 v18, 1.0
	s_and_b64 vcc, exec, s[6:7]
	v_mov_b32_e32 v20, 1.0
	s_cbranch_vccnz .Lcv0_899

	v_lshlrev_b32_e32 v16, 2, v32
	global_load_dword v20, v16, s[14:15]
.Lcv0_899:
	s_load_dwordx2 s[34:35], s[44:45], 0x128
	s_lshr_b32 s33, s33, 22
	s_mulk_i32 s33, 0x58
	s_sub_i32 s31, s31, s33
	s_lshl_b32 s33, s31, 7
	s_and_b32 s33, s33, 0x3ff80
	s_waitcnt lgkmcnt(0)
	s_add_u32 s34, s34, s33
	s_addc_u32 s35, s35, 0
	v_lshl_add_u64 v[16:17], s[34:35], 0, v[0:1]
	v_mad_u64_u32 v[32:33], s[34:35], v32, s29, v[16:17]
	global_load_dwordx4 v[32:35], v[32:33], off
	s_and_b64 vcc, exec, s[6:7]
	s_waitcnt vmcnt(0)
	v_pk_mul_f32 v[32:33], v[32:33], v[20:21] op_sel_hi:[1,0]
	v_pk_mul_f32 v[34:35], v[34:35], v[20:21] op_sel_hi:[1,0]
	ds_write2_b32 v29, v32, v33 offset1:1
	ds_write2_b32 v29, v34, v35 offset0:2 offset1:3
	v_add_lshl_u32 v32, v9, s10, 2
	s_cbranch_vccnz .Lcv0_901

	global_load_dword v18, v32, s[14:15] offset:32
.Lcv0_901:
	v_or_b32_e32 v20, s10, v19
	v_mad_u64_u32 v[34:35], s[34:35], v20, s29, v[16:17]
	global_load_dwordx4 v[34:37], v[34:35], off
	v_mov_b32_e32 v20, 1.0
	s_and_b64 vcc, exec, s[6:7]
	s_waitcnt vmcnt(0)
	v_pk_mul_f32 v[36:37], v[36:37], v[18:19] op_sel_hi:[1,0]
	v_pk_mul_f32 v[34:35], v[34:35], v[18:19] op_sel_hi:[1,0]
	v_mov_b32_e32 v18, 1.0
	ds_write2_b32 v30, v34, v35 offset1:1
	ds_write2_b32 v30, v36, v37 offset0:2 offset1:3
	s_cbranch_vccnz .Lcv0_903

	global_load_dword v18, v32, s[14:15] offset:64
.Lcv0_903:
	v_or_b32_e32 v33, s10, v21
	v_mad_u64_u32 v[34:35], s[34:35], v33, s29, v[16:17]
	global_load_dwordx4 v[34:37], v[34:35], off
	s_and_b64 vcc, exec, s[6:7]
	s_waitcnt vmcnt(0)
	v_pk_mul_f32 v[34:35], v[34:35], v[18:19] op_sel_hi:[1,0]
	v_pk_mul_f32 v[36:37], v[36:37], v[18:19] op_sel_hi:[1,0]
	ds_write2_b32 v31, v34, v35 offset1:1
	ds_write2_b32 v31, v36, v37 offset0:2 offset1:3
	s_cbranch_vccnz .Lcv0_905

	global_load_dword v20, v32, s[14:15] offset:96
.Lcv0_905:
	v_or_b32_e32 v18, s10, v22
	v_mad_u64_u32 v[34:35], s[34:35], v18, s29, v[16:17]
	global_load_dwordx4 v[34:37], v[34:35], off
	v_add_u32_e32 v33, 0x420, v31
	v_mov_b32_e32 v18, 1.0
	s_and_b64 vcc, exec, s[6:7]
	v_add_u32_e32 v40, 0x428, v31
	s_waitcnt vmcnt(0)
	v_pk_mul_f32 v[36:37], v[36:37], v[20:21] op_sel_hi:[1,0]
	v_pk_mul_f32 v[34:35], v[34:35], v[20:21] op_sel_hi:[1,0]
	v_mov_b32_e32 v20, 1.0
	ds_write2_b32 v33, v34, v35 offset1:1
	ds_write2_b32 v40, v36, v37 offset1:1
	s_cbranch_vccnz .Lcv0_907

	global_load_dword v20, v32, s[14:15] offset:128
.Lcv0_907:
	v_or_b32_e32 v33, s10, v23
	v_mad_u64_u32 v[34:35], s[34:35], v33, s29, v[16:17]
	global_load_dwordx4 v[34:37], v[34:35], off
	v_add_u32_e32 v33, 0x840, v31
	s_and_b64 vcc, exec, s[6:7]
	v_add_u32_e32 v40, 0x848, v31
	s_waitcnt vmcnt(0)
	v_pk_mul_f32 v[34:35], v[34:35], v[20:21] op_sel_hi:[1,0]
	v_pk_mul_f32 v[36:37], v[36:37], v[20:21] op_sel_hi:[1,0]
	ds_write2_b32 v33, v34, v35 offset1:1
	ds_write2_b32 v40, v36, v37 offset1:1
	s_cbranch_vccnz .Lcv0_909

	global_load_dword v18, v32, s[14:15] offset:160
.Lcv0_909:
	v_or_b32_e32 v20, s10, v24
	v_mad_u64_u32 v[34:35], s[34:35], v20, s29, v[16:17]
	global_load_dwordx4 v[34:37], v[34:35], off
	v_add_u32_e32 v33, 0xc60, v31
	v_mov_b32_e32 v20, 1.0
	s_and_b64 vcc, exec, s[6:7]
	v_add_u32_e32 v40, 0xc68, v31
	s_waitcnt vmcnt(0)
	v_pk_mul_f32 v[36:37], v[36:37], v[18:19] op_sel_hi:[1,0]
	v_pk_mul_f32 v[34:35], v[34:35], v[18:19] op_sel_hi:[1,0]
	v_mov_b32_e32 v18, 1.0
	ds_write2_b32 v33, v34, v35 offset1:1
	ds_write2_b32 v40, v36, v37 offset1:1
	s_cbranch_vccnz .Lcv0_911

	global_load_dword v18, v32, s[14:15] offset:192
.Lcv0_911:
	v_or_b32_e32 v33, s10, v25
	v_mad_u64_u32 v[34:35], s[34:35], v33, s29, v[16:17]
	global_load_dwordx4 v[34:37], v[34:35], off
	v_add_u32_e32 v33, 0x1080, v31
	s_and_b64 vcc, exec, s[6:7]
	v_add_u32_e32 v40, 0x1088, v31
	s_waitcnt vmcnt(0)
	v_pk_mul_f32 v[34:35], v[34:35], v[18:19] op_sel_hi:[1,0]
	v_pk_mul_f32 v[36:37], v[36:37], v[18:19] op_sel_hi:[1,0]
	ds_write2_b32 v33, v34, v35 offset1:1
	ds_write2_b32 v40, v36, v37 offset1:1
	s_cbranch_vccnz .Lcv0_913

	global_load_dword v20, v32, s[14:15] offset:224

.Lcv0_914:
	s_add_i32 s31, s2, 0xffffee80
	s_cmpk_gt_u32 s31, 0x57f
	s_cbranch_scc1 .Lcv0_932

	s_and_b32 s33, s31, 0xffff
	s_mul_i32 s33, s33, 0xba2f
	s_lshr_b32 s10, s33, 16
	s_and_b32 s10, s10, 0xffc0
	v_or_b32_e32 v32, s10, v9
	v_mov_b32_e32 v18, 1.0
	s_and_b64 vcc, exec, s[6:7]
	v_mov_b32_e32 v20, 1.0
	s_cbranch_vccnz .Lcv0_917

	v_lshlrev_b32_e32 v16, 2, v32
	global_load_dword v20, v16, s[14:15]
.Lcv0_917:
	s_load_dwordx2 s[34:35], s[44:45], 0x130
	s_lshr_b32 s33, s33, 22
	s_mulk_i32 s33, 0x58
	s_sub_i32 s31, s31, s33
	s_lshl_b32 s33, s31, 7
	s_and_b32 s33, s33, 0x3ff80
	s_waitcnt lgkmcnt(0)
	s_add_u32 s34, s34, s33
	s_addc_u32 s35, s35, 0
	v_lshl_add_u64 v[16:17], s[34:35], 0, v[0:1]
	v_mad_u64_u32 v[32:33], s[34:35], v32, s29, v[16:17]
	global_load_dwordx4 v[32:35], v[32:33], off
	s_and_b64 vcc, exec, s[6:7]
	s_waitcnt vmcnt(0)
	v_pk_mul_f32 v[32:33], v[32:33], v[20:21] op_sel_hi:[1,0]
	v_pk_mul_f32 v[34:35], v[34:35], v[20:21] op_sel_hi:[1,0]
	ds_write2_b32 v29, v32, v33 offset1:1
	ds_write2_b32 v29, v34, v35 offset0:2 offset1:3
	v_add_lshl_u32 v32, v9, s10, 2
	s_cbranch_vccnz .Lcv0_919

	global_load_dword v18, v32, s[14:15] offset:32

.Lcv0_932:
	s_add_i32 s6, s2, 0xffffe900
	s_cmpk_gt_u32 s6, 0x57f
	v_add_u32_e32 v16, 0x420, v29
	v_add_u32_e32 v17, 0x428, v29
	v_add_u32_e32 v18, 0x840, v29
	v_add_u32_e32 v20, 0x848, v29
	v_add_u32_e32 v32, 0xc60, v29
	v_add_u32_e32 v33, 0xc68, v29
	v_add_u32_e32 v34, 0x1080, v29
	v_add_u32_e32 v35, 0x1088, v29
	v_add_u32_e32 v36, 0x14a0, v29
	v_add_u32_e32 v37, 0x14a8, v29
	v_add_u32_e32 v40, 0x18c0, v29
	v_add_u32_e32 v41, 0x18c8, v29
	v_add_u32_e32 v42, 0x1ce0, v29
	v_add_u32_e32 v43, 0x1ce8, v29
	s_cbranch_scc1 .Lcv0_934

	s_load_dwordx2 s[34:35], s[44:45], 0x138
	s_add_i32 s6, s22, 0xfffde200
	s_and_b32 s7, s6, 0xfc0
	s_lshl_b32 s6, s2, 5
	s_and_b32 s6, s6, 0x3e0
	s_lshl_b32 s10, s6, 2
	s_waitcnt lgkmcnt(0)
	s_add_u32 s34, s34, s10
	s_addc_u32 s35, s35, 0
	v_or_b32_e32 v44, s7, v9
	v_or_b32_e32 v46, s7, v19
	v_or_b32_e32 v52, s7, v21
	v_or_b32_e32 v54, s7, v22
	v_or_b32_e32 v60, s7, v23
	v_or_b32_e32 v62, s7, v24
	v_lshl_add_u64 v[76:77], s[34:35], 0, v[0:1]
	v_lshlrev_b32_e32 v44, 12, v44
	v_mov_b32_e32 v45, v1
	v_lshlrev_b32_e32 v46, 12, v46
	v_mov_b32_e32 v47, v1
	v_lshlrev_b32_e32 v52, 12, v52
	v_mov_b32_e32 v53, v1
	v_lshlrev_b32_e32 v54, 12, v54
	v_mov_b32_e32 v55, v1
	v_lshlrev_b32_e32 v60, 12, v60
	v_mov_b32_e32 v61, v1
	v_lshlrev_b32_e32 v62, 12, v62
	v_mov_b32_e32 v63, v1
	v_lshl_add_u64 v[44:45], v[76:77], 0, v[44:45]
	v_lshl_add_u64 v[48:49], v[76:77], 0, v[46:47]
	v_lshl_add_u64 v[52:53], v[76:77], 0, v[52:53]
	v_lshl_add_u64 v[56:57], v[76:77], 0, v[54:55]
	v_lshl_add_u64 v[60:61], v[76:77], 0, v[60:61]
	v_lshl_add_u64 v[68:69], v[76:77], 0, v[62:63]
	global_load_dwordx4 v[44:47], v[44:45], off
	s_nop 0
	global_load_dwordx4 v[48:51], v[48:49], off
	s_nop 0
	global_load_dwordx4 v[52:55], v[52:53], off
	s_nop 0
	global_load_dwordx4 v[56:59], v[56:57], off
	s_nop 0
	global_load_dwordx4 v[60:63], v[60:61], off
	s_nop 0
	global_load_dwordx4 v[68:71], v[68:69], off
	v_or_b32_e32 v65, s7, v25
	v_lshlrev_b32_e32 v72, 12, v65
	v_mov_b32_e32 v73, v1
	v_lshl_add_u64 v[72:73], v[76:77], 0, v[72:73]
	v_or_b32_e32 v65, s7, v26
	global_load_dwordx4 v[72:75], v[72:73], off
	v_lshlrev_b32_e32 v78, 12, v65
	v_mov_b32_e32 v79, v1
	v_lshl_add_u64 v[76:77], v[76:77], 0, v[78:79]
	global_load_dwordx4 v[76:79], v[76:77], off
	s_lshl_b32 s10, s7, 1
	s_waitcnt vmcnt(7)
	ds_write2_b32 v29, v44, v45 offset1:1
	ds_write2_b32 v29, v46, v47 offset0:2 offset1:3
	s_waitcnt vmcnt(6)
	ds_write2_b32 v16, v48, v49 offset1:1
	ds_write2_b32 v17, v50, v51 offset1:1
	s_waitcnt vmcnt(5)
	ds_write2_b32 v18, v52, v53 offset1:1
	ds_write2_b32 v20, v54, v55 offset1:1
	s_waitcnt vmcnt(4)
	ds_write2_b32 v32, v56, v57 offset1:1
	ds_write2_b32 v33, v58, v59 offset1:1
	s_waitcnt vmcnt(3)
	ds_write2_b32 v34, v60, v61 offset1:1
	ds_write2_b32 v35, v62, v63 offset1:1
	s_waitcnt vmcnt(2)
	ds_write2_b32 v36, v68, v69 offset1:1
	ds_write2_b32 v37, v70, v71 offset1:1
	s_waitcnt vmcnt(1)
	ds_write2_b32 v40, v72, v73 offset1:1
	ds_write2_b32 v41, v74, v75 offset1:1
	s_waitcnt vmcnt(0)
	ds_write2_b32 v42, v76, v77 offset1:1
	ds_write2_b32 v43, v78, v79 offset1:1
	s_waitcnt lgkmcnt(0)
	ds_read2_b32 v[44:45], v27 offset1:33
	s_waitcnt lgkmcnt(0)
	v_cvt_pk_bf16_f32 v44, v44, v45
	ds_read2_b32 v[46:47], v27 offset0:66 offset1:99
	s_waitcnt lgkmcnt(0)
	v_cvt_pk_bf16_f32 v45, v46, v47
	ds_read2_b32 v[46:47], v27 offset0:132 offset1:165
	s_waitcnt lgkmcnt(0)
	v_cvt_pk_bf16_f32 v46, v46, v47
	v_or_b32_e32 v47, s6, v9
	v_mov_b32_e32 v51, v1
	v_mul_u32_u24_e32 v50, 0x1600, v47
	v_lshl_add_u64 v[52:53], v[12:13], 0, s[10:11]
	ds_read2_b32 v[48:49], v27 offset0:198 offset1:231
	s_waitcnt lgkmcnt(0)
	v_cvt_pk_bf16_f32 v47, v48, v49
	v_lshl_add_u64 v[50:51], v[52:53], 0, v[50:51]
	ds_read2_b32 v[48:49], v27 offset0:8 offset1:41
	global_store_dwordx4 v[50:51], v[44:47], off
	v_or_b32_e32 v50, s6, v19
	v_mov_b32_e32 v51, v1
	s_waitcnt lgkmcnt(0)
	v_cvt_pk_bf16_f32 v44, v48, v49
	ds_read2_b32 v[46:47], v27 offset0:74 offset1:107
	s_waitcnt lgkmcnt(0)
	v_cvt_pk_bf16_f32 v45, v46, v47
	ds_read2_b32 v[46:47], v27 offset0:140 offset1:173
	v_mul_u32_u24_e32 v50, 0x1600, v50
	s_waitcnt lgkmcnt(0)
	v_cvt_pk_bf16_f32 v46, v46, v47
	ds_read2_b32 v[48:49], v27 offset0:206 offset1:239
	s_waitcnt lgkmcnt(0)
	v_cvt_pk_bf16_f32 v47, v48, v49
	v_lshl_add_u64 v[50:51], v[52:53], 0, v[50:51]
	ds_read2_b32 v[48:49], v27 offset0:16 offset1:49
	global_store_dwordx4 v[50:51], v[44:47], off
	v_or_b32_e32 v50, s6, v21
	v_mov_b32_e32 v51, v1
	s_waitcnt lgkmcnt(0)
	v_cvt_pk_bf16_f32 v44, v48, v49
	ds_read2_b32 v[46:47], v27 offset0:82 offset1:115
	s_waitcnt lgkmcnt(0)
	v_cvt_pk_bf16_f32 v45, v46, v47
	ds_read2_b32 v[46:47], v27 offset0:148 offset1:181
	v_mul_u32_u24_e32 v50, 0x1600, v50
	s_waitcnt lgkmcnt(0)
	v_cvt_pk_bf16_f32 v46, v46, v47
	ds_read2_b32 v[48:49], v27 offset0:214 offset1:247
	s_waitcnt lgkmcnt(0)
	v_cvt_pk_bf16_f32 v47, v48, v49
	v_lshl_add_u64 v[50:51], v[52:53], 0, v[50:51]
	ds_read2_b32 v[48:49], v27 offset0:24 offset1:57
	global_store_dwordx4 v[50:51], v[44:47], off
	v_mov_b32_e32 v51, v1
	s_waitcnt lgkmcnt(0)
	v_cvt_pk_bf16_f32 v44, v48, v49
	ds_read2_b32 v[46:47], v27 offset0:90 offset1:123
	s_waitcnt lgkmcnt(0)
	v_cvt_pk_bf16_f32 v45, v46, v47
	ds_read2_b32 v[46:47], v27 offset0:156 offset1:189
	s_waitcnt lgkmcnt(0)
	v_cvt_pk_bf16_f32 v46, v46, v47
	v_or_b32_e32 v47, s6, v22
	ds_read2_b32 v[48:49], v27 offset0:222 offset1:255
	v_mul_u32_u24_e32 v50, 0x1600, v47
	s_waitcnt lgkmcnt(0)
	v_cvt_pk_bf16_f32 v47, v48, v49
	v_lshl_add_u64 v[48:49], v[52:53], 0, v[50:51]
	global_store_dwordx4 v[48:49], v[44:47], off
	s_waitcnt lgkmcnt(0)
.Lcv0_934:
	s_and_b32 s6, s2, 0xffffffe0
	s_cmpk_lg_i32 s6, 0x1c80
	s_cbranch_scc1 .Lcv0_868

	s_load_dwordx2 s[34:35], s[44:45], 0x78
	s_lshl_b32 s6, s2, 5
	s_and_b32 s6, s6, 0xe0
	s_and_b32 s7, s24, 0xc0
	s_lshl_b32 s10, s6, 2
	s_waitcnt lgkmcnt(0)
	s_add_u32 s34, s34, s10
	s_addc_u32 s35, s35, 0
	v_or_b32_e32 v44, s7, v9
	v_or_b32_e32 v46, s7, v19
	v_or_b32_e32 v52, s7, v21
	v_or_b32_e32 v54, s7, v22
	v_or_b32_e32 v60, s7, v23
	v_or_b32_e32 v62, s7, v24
	v_lshl_add_u64 v[76:77], s[34:35], 0, v[0:1]
	v_lshlrev_b32_e32 v44, 10, v44
	v_mov_b32_e32 v45, v1
	v_lshlrev_b32_e32 v46, 10, v46
	v_mov_b32_e32 v47, v1
	v_lshlrev_b32_e32 v52, 10, v52
	v_mov_b32_e32 v53, v1
	v_lshlrev_b32_e32 v54, 10, v54
	v_mov_b32_e32 v55, v1
	v_lshlrev_b32_e32 v60, 10, v60
	v_mov_b32_e32 v61, v1
	v_lshlrev_b32_e32 v62, 10, v62
	v_mov_b32_e32 v63, v1
	v_lshl_add_u64 v[44:45], v[76:77], 0, v[44:45]
	v_lshl_add_u64 v[48:49], v[76:77], 0, v[46:47]
	v_lshl_add_u64 v[52:53], v[76:77], 0, v[52:53]
	v_lshl_add_u64 v[56:57], v[76:77], 0, v[54:55]
	v_lshl_add_u64 v[60:61], v[76:77], 0, v[60:61]
	v_lshl_add_u64 v[68:69], v[76:77], 0, v[62:63]
	global_load_dwordx4 v[44:47], v[44:45], off
	s_nop 0
	global_load_dwordx4 v[48:51], v[48:49], off
	s_nop 0
	global_load_dwordx4 v[52:55], v[52:53], off
	s_nop 0
	global_load_dwordx4 v[56:59], v[56:57], off
	s_nop 0
	global_load_dwordx4 v[60:63], v[60:61], off
	s_nop 0
	global_load_dwordx4 v[68:71], v[68:69], off
	v_or_b32_e32 v65, s7, v25
	v_lshlrev_b32_e32 v72, 10, v65
	v_mov_b32_e32 v73, v1
	v_lshl_add_u64 v[72:73], v[76:77], 0, v[72:73]
	v_or_b32_e32 v65, s7, v26
	global_load_dwordx4 v[72:75], v[72:73], off
	v_lshlrev_b32_e32 v78, 10, v65
	v_mov_b32_e32 v79, v1
	v_lshl_add_u64 v[76:77], v[76:77], 0, v[78:79]
	global_load_dwordx4 v[76:79], v[76:77], off
	s_lshl_b32 s10, s7, 1
	s_waitcnt vmcnt(7)
	ds_write2_b32 v29, v44, v45 offset1:1
	ds_write2_b32 v29, v46, v47 offset0:2 offset1:3
	s_waitcnt vmcnt(6)
	ds_write2_b32 v16, v48, v49 offset1:1
	ds_write2_b32 v17, v50, v51 offset1:1
	s_waitcnt vmcnt(5)
	ds_write2_b32 v18, v52, v53 offset1:1
	ds_write2_b32 v20, v54, v55 offset1:1
	s_waitcnt vmcnt(4)
	ds_write2_b32 v32, v56, v57 offset1:1
	ds_write2_b32 v33, v58, v59 offset1:1
	s_waitcnt vmcnt(3)
	ds_write2_b32 v34, v60, v61 offset1:1
	ds_write2_b32 v35, v62, v63 offset1:1
	s_waitcnt vmcnt(2)
	ds_write2_b32 v36, v68, v69 offset1:1
	ds_write2_b32 v37, v70, v71 offset1:1
	s_waitcnt vmcnt(1)
	ds_write2_b32 v40, v72, v73 offset1:1
	ds_write2_b32 v41, v74, v75 offset1:1
	s_waitcnt vmcnt(0)
	ds_write2_b32 v42, v76, v77 offset1:1
	ds_write2_b32 v43, v78, v79 offset1:1
	s_waitcnt lgkmcnt(0)
	ds_read2_b32 v[16:17], v27 offset1:33
	s_waitcnt lgkmcnt(0)
	v_cvt_pk_bf16_f32 v32, v16, v17
	ds_read2_b32 v[16:17], v27 offset0:66 offset1:99
	s_waitcnt lgkmcnt(0)
	v_cvt_pk_bf16_f32 v33, v16, v17
	ds_read2_b32 v[16:17], v27 offset0:132 offset1:165
	v_or_b32_e32 v18, s6, v9
	s_waitcnt lgkmcnt(0)
	v_cvt_pk_bf16_f32 v34, v16, v17
	ds_read2_b32 v[16:17], v27 offset0:198 offset1:231
	v_mov_b32_e32 v37, v1
	v_lshlrev_b32_e32 v36, 9, v18
	v_lshl_add_u64 v[40:41], v[14:15], 0, s[10:11]
	s_waitcnt lgkmcnt(0)
	v_cvt_pk_bf16_f32 v35, v16, v17
	ds_read2_b32 v[16:17], v27 offset0:8 offset1:41
	v_lshl_add_u64 v[36:37], v[40:41], 0, v[36:37]
	global_store_dwordx4 v[36:37], v[32:35], off
	v_or_b32_e32 v18, s6, v19
	v_mov_b32_e32 v37, v1
	s_waitcnt lgkmcnt(0)
	v_cvt_pk_bf16_f32 v32, v16, v17
	ds_read2_b32 v[16:17], v27 offset0:74 offset1:107
	s_waitcnt lgkmcnt(0)
	v_cvt_pk_bf16_f32 v33, v16, v17
	ds_read2_b32 v[16:17], v27 offset0:140 offset1:173
	s_waitcnt lgkmcnt(0)
	v_cvt_pk_bf16_f32 v34, v16, v17
	ds_read2_b32 v[16:17], v27 offset0:206 offset1:239
	v_lshlrev_b32_e32 v36, 9, v18
	s_waitcnt lgkmcnt(0)
	v_cvt_pk_bf16_f32 v35, v16, v17
	ds_read2_b32 v[16:17], v27 offset0:16 offset1:49
	v_lshl_add_u64 v[36:37], v[40:41], 0, v[36:37]
	global_store_dwordx4 v[36:37], v[32:35], off
	v_or_b32_e32 v18, s6, v21
	v_mov_b32_e32 v37, v1
	s_waitcnt lgkmcnt(0)
	v_cvt_pk_bf16_f32 v32, v16, v17
	ds_read2_b32 v[16:17], v27 offset0:82 offset1:115
	s_waitcnt lgkmcnt(0)
	v_cvt_pk_bf16_f32 v33, v16, v17
	ds_read2_b32 v[16:17], v27 offset0:148 offset1:181
	s_waitcnt lgkmcnt(0)
	v_cvt_pk_bf16_f32 v34, v16, v17
	ds_read2_b32 v[16:17], v27 offset0:214 offset1:247
	v_lshlrev_b32_e32 v36, 9, v18
	s_waitcnt lgkmcnt(0)
	v_cvt_pk_bf16_f32 v35, v16, v17
	ds_read2_b32 v[16:17], v27 offset0:24 offset1:57
	v_lshl_add_u64 v[36:37], v[40:41], 0, v[36:37]
	global_store_dwordx4 v[36:37], v[32:35], off
	v_or_b32_e32 v18, s6, v22
	v_mov_b32_e32 v37, v1
	s_waitcnt lgkmcnt(0)
	v_cvt_pk_bf16_f32 v32, v16, v17
	ds_read2_b32 v[16:17], v27 offset0:90 offset1:123
	s_waitcnt lgkmcnt(0)
	v_cvt_pk_bf16_f32 v33, v16, v17
	ds_read2_b32 v[16:17], v27 offset0:156 offset1:189
	s_waitcnt lgkmcnt(0)
	v_cvt_pk_bf16_f32 v34, v16, v17
	ds_read2_b32 v[16:17], v27 offset0:222 offset1:255
	v_lshlrev_b32_e32 v36, 9, v18
	s_waitcnt lgkmcnt(0)
	v_cvt_pk_bf16_f32 v35, v16, v17
	v_lshl_add_u64 v[16:17], v[40:41], 0, v[36:37]
	global_store_dwordx4 v[16:17], v[32:35], off
	s_waitcnt lgkmcnt(0)
	s_branch .Lcv0_868

.Lcv0_937:
.Lcv0_skip:
.LBB0_435:
	s_cmp_lt_i32 s43, 5
	s_cbranch_scc1 .LBB0_489
	s_waitcnt vmcnt(0)
	s_barrier
	s_and_saveexec_b64 s[4:5], s[86:87]
	s_cbranch_execz .LBB0_488
	s_add_i32 s1, 0, 0x23fc0
	v_mov_b32_e32 v0, s1
	s_waitcnt vmcnt(0) expcnt(0) lgkmcnt(0)
	ds_read_b32 v2, v0
	s_add_i32 s1, 0, 0x23fc4
	v_mov_b32_e32 v0, s1
	ds_read_b32 v0, v0
	s_waitcnt lgkmcnt(1)
	v_cmp_ne_u32_e32 vcc, 0, v2
	s_cbranch_vccnz .LBB0_452
	s_add_u32 s6, s40, 0x1000
	s_load_dwordx2 s[2:3], s[10:11], 0x4
	s_addc_u32 s7, s41, 0
	s_add_u32 s8, s40, 0x1100
	s_addc_u32 s9, s41, 0
	s_add_u32 s10, s40, 0x1200
	s_addc_u32 s11, s41, 0
	s_waitcnt lgkmcnt(0)
	s_mul_i32 s0, s2, s0
	s_add_u32 s12, s40, 0x1300
	s_mul_i32 s0, s0, s3
	s_addc_u32 s13, s41, 0
	s_mov_b32 s1, 1
	v_mov_b32_e32 v16, 0
	s_branch .LBB0_440

.LBB0_869:
	s_cmpk_lt_i32 s2, 0xc00
	s_cbranch_scc1 .LBB0_868
	s_cmpk_gt_u32 s2, 0x7ff
	s_cbranch_scc1 .LBB0_884
	s_lshr_b32 s6, s2, 1
	s_and_b32 s10, s6, 0x3c0
	v_or_b32_e32 v32, s10, v9
	v_mov_b32_e32 v18, 1.0
	s_and_b64 vcc, exec, s[4:5]
	v_mov_b32_e32 v20, 1.0
	s_cbranch_vccnz .LBB0_872
	v_lshlrev_b32_e32 v16, 2, v32
	global_load_dword v20, v16, s[12:13]

.LBB0_2143:
	s_waitcnt vmcnt(0)
	s_barrier
	s_cmpk_lt_i32 s90, 0x80
	s_cbranch_scc1 .Lcv1_skip
	s_mov_b64 s[44:45], s[88:89]
	s_load_dwordx2 s[46:47], s[88:89], 0x150
	s_sub_i32 s61, s90, 64
	s_movk_i32 s62, 0xc0
	s_lshr_b32 s63, s91, 6
	v_mbcnt_hi_u32_b32 v66, -1, v210
	v_lshlrev_b32_e32 v8, 2, v66
	s_waitcnt lgkmcnt(0)
	s_load_dwordx2 s[4:5], s[44:45], 0x28
	s_load_dwordx2 s[6:7], s[44:45], 0x120
	s_lshl_b32 s2, s63, 14
	s_add_i32 s10, s2, 0
	s_lshl_b32 s2, s61, 3
	s_add_i32 s2, s2, s63
	s_lshl_b32 s20, s62, 3
	s_addk_i32 s2, 0xfe00
	s_add_i32 s3, s20, 0xfffffe00
	s_waitcnt lgkmcnt(0)
	s_add_u32 s12, s4, 0x1000
	s_addc_u32 s13, s5, 0
	s_add_u32 s14, s6, 0x1000
	s_addc_u32 s15, s7, 0
	s_cmp_lg_u64 s[4:5], 0
	s_cselect_b64 s[4:5], -1, 0
	s_cmp_lg_u64 s[6:7], 0
	v_lshrrev_b32_e32 v9, 3, v66
	s_movk_i32 s6, 0x84
	v_mov_b32_e32 v0, 0x420
	v_mad_u32_u24 v18, v9, s6, v0
	v_mov_b32_e32 v0, 0x840
	v_mad_u32_u24 v23, v9, s6, v0
	v_lshlrev_b32_e32 v0, 3, v66
	v_and_b32_e32 v0, 56, v0
	v_mov_b32_e32 v1, 0
	v_mul_u32_u24_e32 v4, 0x84, v0
	v_lshlrev_b32_e32 v0, 1, v0
	v_lshl_add_u64 v[14:15], s[46:47], 0, v[0:1]
	v_lshlrev_b32_e32 v0, 2, v9
	s_mov_b64 s[6:7], 0xe00000
	v_add3_u32 v29, s10, v4, v0
	v_lshl_add_u64 v[4:5], v[14:15], 0, s[6:7]
	s_mov_b64 s[6:7], 0xc00000
	v_lshl_add_u64 v[6:7], v[14:15], 0, s[6:7]
	s_mov_b64 s[6:7], 0x1000000
	v_lshl_add_u64 v[10:11], v[14:15], 0, s[6:7]
	s_mov_b64 s[6:7], 0x1b00000
	s_mov_b64 s[18:19], 0x400000
	v_lshl_add_u64 v[12:13], v[14:15], 0, s[6:7]
	s_mov_b64 s[6:7], 0x2080000
	s_cselect_b64 s[16:17], -1, 0
	v_and_b32_e32 v16, 28, v8
	v_lshl_add_u64 v[2:3], v[14:15], 0, s[18:19]
	v_lshl_add_u64 v[14:15], v[14:15], 0, s[6:7]
	s_lshl_b32 s6, s61, 4
	s_lshl_b32 s7, s63, 1
	v_lshl_add_u32 v19, v16, 2, s10
	v_mul_u32_u24_e32 v17, 0x84, v9
	s_add_i32 s6, s6, s7
	s_lshl_b32 s27, s62, 4
	s_lshl_b32 s29, s62, 6
	v_cndmask_b32_e64 v0, 0, 1, s[4:5]
	s_mov_b32 s11, 0
	v_or_b32_e32 v21, 8, v9
	v_or_b32_e32 v22, 16, v9
	v_or_b32_e32 v24, 24, v9
	v_or_b32_e32 v25, 32, v9
	v_or_b32_e32 v26, 40, v9
	v_or_b32_e32 v27, 48, v9
	v_or_b32_e32 v28, 56, v9
	v_bitop3_b32 v30, v9, 15, 24 bitop3:0xc8
	s_add_i32 s26, s6, 0x1ec00
	s_addk_i32 s27, 0xfc00
	s_lshl_b32 s28, s2, 3
	s_addk_i32 s29, 0xf000
	s_sub_i32 s30, 0, s20
	v_cmp_ne_u32_e64 s[4:5], 1, v0
	s_mov_b64 s[20:21], 0x1802000
	s_movk_i32 s31, 0x6000
	v_add_u32_e32 v31, v19, v17
	v_add_u32_e32 v32, v19, v18
	s_mov_b32 s33, 0x80000
	s_mov_b64 s[22:23], 0xb00000
	s_movk_i32 s34, 0x2c00
	s_mov_b32 s35, 0x40000
	s_mov_b64 s[24:25], 0x40000
	v_lshlrev_b32_e32 v0, 2, v16
	s_branch .Lcv1_2578

.Lcv1_2578:
	s_cmpk_gt_i32 s2, 0xbff
	s_cbranch_scc1 .Lcv1_2643
	s_cmpk_gt_u32 s2, 0x7ff
	s_cbranch_scc1 .Lcv1_2597

	s_lshr_b32 s6, s2, 1
	s_and_b32 s6, s6, 0x3c0
	v_or_b32_e32 v33, s6, v9
	v_mov_b32_e32 v18, 1.0
	s_and_b64 vcc, exec, s[4:5]
	v_mov_b32_e32 v20, 1.0
	s_cbranch_vccnz .Lcv1_2581

	v_lshlrev_b32_e32 v16, 2, v33
	global_load_dword v20, v16, s[12:13]
.Lcv1_2581:
	s_load_dwordx2 s[36:37], s[44:45], 0x30
	s_lshl_b32 s7, s2, 5
	s_and_b32 s7, s7, 0xfe0
	s_lshl_b32 s10, s7, 2
	s_waitcnt lgkmcnt(0)
	s_add_u32 s36, s36, s10
	s_addc_u32 s37, s37, 0
	v_lshl_add_u64 v[16:17], s[36:37], 0, v[0:1]
	v_lshl_add_u64 v[16:17], v[16:17], 0, s[20:21]
	v_mad_u64_u32 v[34:35], s[36:37], v33, s31, v[16:17]
	global_load_dwordx4 v[34:37], v[34:35], off
	s_and_b64 vcc, exec, s[4:5]
	s_waitcnt vmcnt(0)
	v_pk_mul_f32 v[36:37], v[36:37], v[20:21] op_sel_hi:[1,0]
	v_pk_mul_f32 v[34:35], v[34:35], v[20:21] op_sel_hi:[1,0]
	v_or_b32_e32 v20, s6, v21
	ds_write2_b32 v31, v34, v35 offset1:1
	ds_write2_b32 v31, v36, v37 offset0:2 offset1:3
	s_cbranch_vccnz .Lcv1_2583

	v_lshlrev_b32_e32 v18, 2, v20
	global_load_dword v18, v18, s[12:13]
.Lcv1_2583:
	v_mad_u64_u32 v[34:35], s[36:37], v20, s31, v[16:17]
	global_load_dwordx4 v[34:37], v[34:35], off
	v_or_b32_e32 v33, s6, v22
	v_mov_b32_e32 v20, 1.0
	s_and_b64 vcc, exec, s[4:5]
	s_waitcnt vmcnt(0)
	v_pk_mul_f32 v[36:37], v[36:37], v[18:19] op_sel_hi:[1,0]
	v_pk_mul_f32 v[34:35], v[34:35], v[18:19] op_sel_hi:[1,0]
	v_mov_b32_e32 v18, 1.0
	ds_write2_b32 v32, v34, v35 offset1:1
	ds_write2_b32 v32, v36, v37 offset0:2 offset1:3
	s_cbranch_vccnz .Lcv1_2585

	v_lshlrev_b32_e32 v18, 2, v33
	global_load_dword v18, v18, s[12:13]
.Lcv1_2585:
	v_mad_u64_u32 v[34:35], s[36:37], v33, s31, v[16:17]
	global_load_dwordx4 v[34:37], v[34:35], off
	v_add_u32_e32 v33, v19, v23
	s_and_b64 vcc, exec, s[4:5]
	s_waitcnt vmcnt(0)
	v_pk_mul_f32 v[36:37], v[36:37], v[18:19] op_sel_hi:[1,0]
	v_pk_mul_f32 v[34:35], v[34:35], v[18:19] op_sel_hi:[1,0]
	v_or_b32_e32 v18, s6, v24
	ds_write2_b32 v33, v34, v35 offset1:1
	ds_write2_b32 v33, v36, v37 offset0:2 offset1:3
	s_cbranch_vccnz .Lcv1_2587

	v_lshlrev_b32_e32 v20, 2, v18
	global_load_dword v20, v20, s[12:13]
.Lcv1_2587:
	v_mad_u64_u32 v[34:35], s[36:37], v18, s31, v[16:17]
	global_load_dwordx4 v[40:43], v[34:35], off
	v_add_u32_e32 v35, 0x420, v33
	v_or_b32_e32 v34, s6, v25
	v_mov_b32_e32 v18, 1.0
	s_and_b64 vcc, exec, s[4:5]
	v_add_u32_e32 v44, 0x428, v33
	s_waitcnt vmcnt(0)
	v_pk_mul_f32 v[36:37], v[42:43], v[20:21] op_sel_hi:[1,0]
	v_pk_mul_f32 v[40:41], v[40:41], v[20:21] op_sel_hi:[1,0]
	v_mov_b32_e32 v20, 1.0
	ds_write2_b32 v35, v40, v41 offset1:1
	ds_write2_b32 v44, v36, v37 offset1:1
	s_cbranch_vccnz .Lcv1_2589

	v_lshlrev_b32_e32 v20, 2, v34
	global_load_dword v20, v20, s[12:13]
.Lcv1_2589:
	v_mad_u64_u32 v[34:35], s[36:37], v34, s31, v[16:17]
	global_load_dwordx4 v[34:37], v[34:35], off
	v_add_u32_e32 v40, 0x840, v33
	s_and_b64 vcc, exec, s[4:5]
	v_add_u32_e32 v41, 0x848, v33
	s_waitcnt vmcnt(0)
	v_pk_mul_f32 v[36:37], v[36:37], v[20:21] op_sel_hi:[1,0]
	v_pk_mul_f32 v[34:35], v[34:35], v[20:21] op_sel_hi:[1,0]
	v_or_b32_e32 v20, s6, v26
	ds_write2_b32 v40, v34, v35 offset1:1
	ds_write2_b32 v41, v36, v37 offset1:1
	s_cbranch_vccnz .Lcv1_2591

	v_lshlrev_b32_e32 v18, 2, v20
	global_load_dword v18, v18, s[12:13]
.Lcv1_2591:
	v_mad_u64_u32 v[34:35], s[36:37], v20, s31, v[16:17]
	global_load_dwordx4 v[40:43], v[34:35], off
	v_add_u32_e32 v35, 0xc60, v33
	v_or_b32_e32 v34, s6, v27
	v_mov_b32_e32 v20, 1.0
	s_and_b64 vcc, exec, s[4:5]
	v_add_u32_e32 v44, 0xc68, v33
	s_waitcnt vmcnt(0)
	v_pk_mul_f32 v[36:37], v[42:43], v[18:19] op_sel_hi:[1,0]
	v_pk_mul_f32 v[40:41], v[40:41], v[18:19] op_sel_hi:[1,0]
	v_mov_b32_e32 v18, 1.0
	ds_write2_b32 v35, v40, v41 offset1:1
	ds_write2_b32 v44, v36, v37 offset1:1
	s_cbranch_vccnz .Lcv1_2593

	v_lshlrev_b32_e32 v18, 2, v34
	global_load_dword v18, v18, s[12:13]
.Lcv1_2593:
	v_mad_u64_u32 v[34:35], s[36:37], v34, s31, v[16:17]
	global_load_dwordx4 v[34:37], v[34:35], off
	v_add_u32_e32 v40, 0x1080, v33
	s_and_b64 vcc, exec, s[4:5]
	v_add_u32_e32 v41, 0x1088, v33
	s_waitcnt vmcnt(0)
	v_pk_mul_f32 v[36:37], v[36:37], v[18:19] op_sel_hi:[1,0]
	v_pk_mul_f32 v[34:35], v[34:35], v[18:19] op_sel_hi:[1,0]
	v_or_b32_e32 v18, s6, v28
	ds_write2_b32 v40, v34, v35 offset1:1
	ds_write2_b32 v41, v36, v37 offset1:1
	s_cbranch_vccnz .Lcv1_2595

	v_lshlrev_b32_e32 v20, 2, v18
	global_load_dword v20, v20, s[12:13]

.Lcv1_2598:
	s_cmpk_eq_i32 s36, 0xa00
	s_cbranch_scc0 .Lcv1_2600

	s_load_dwordx2 s[48:49], s[44:45], 0x118
	s_add_i32 s6, s26, 0xfffffc00
	s_and_b32 s7, s6, 0x1ffc0
	s_lshl_b32 s6, s2, 5
	v_or_b32_e32 v18, s7, v9
	s_and_b32 s6, s6, 0x3e0
	v_lshlrev_b32_e32 v34, 12, v18
	v_or_b32_e32 v18, s7, v21
	s_lshl_b32 s10, s6, 2
	v_lshlrev_b32_e32 v36, 12, v18
	v_or_b32_e32 v18, s7, v22
	s_waitcnt lgkmcnt(0)
	s_add_u32 s48, s48, s10
	v_lshlrev_b32_e32 v44, 12, v18
	v_or_b32_e32 v18, s7, v24
	s_addc_u32 s49, s49, 0
	v_lshlrev_b32_e32 v46, 12, v18
	v_or_b32_e32 v18, s7, v25
	v_lshl_add_u64 v[16:17], s[48:49], 0, v[0:1]
	v_lshlrev_b32_e32 v52, 12, v18
	v_or_b32_e32 v18, s7, v26
	v_lshl_add_u64 v[16:17], v[16:17], 0, s[18:19]
	v_mov_b32_e32 v35, v1
	v_mov_b32_e32 v37, v1
	v_mov_b32_e32 v45, v1
	v_mov_b32_e32 v47, v1
	v_mov_b32_e32 v53, v1
	v_lshlrev_b32_e32 v54, 12, v18
	v_mov_b32_e32 v55, v1
	v_lshl_add_u64 v[34:35], v[16:17], 0, v[34:35]
	v_lshl_add_u64 v[40:41], v[16:17], 0, v[36:37]
	v_lshl_add_u64 v[44:45], v[16:17], 0, v[44:45]
	v_lshl_add_u64 v[48:49], v[16:17], 0, v[46:47]
	v_lshl_add_u64 v[52:53], v[16:17], 0, v[52:53]
	v_lshl_add_u64 v[56:57], v[16:17], 0, v[54:55]
	global_load_dwordx4 v[34:37], v[34:35], off
	s_nop 0
	global_load_dwordx4 v[40:43], v[40:41], off
	s_nop 0
	global_load_dwordx4 v[44:47], v[44:45], off
	s_nop 0
	global_load_dwordx4 v[48:51], v[48:49], off
	s_nop 0
	global_load_dwordx4 v[52:55], v[52:53], off
	s_nop 0
	global_load_dwordx4 v[56:59], v[56:57], off
	v_or_b32_e32 v18, s7, v27
	v_lshlrev_b32_e32 v60, 12, v18
	v_mov_b32_e32 v61, v1
	v_lshl_add_u64 v[60:61], v[16:17], 0, v[60:61]
	v_or_b32_e32 v18, s7, v28
	global_load_dwordx4 v[60:63], v[60:61], off
	v_lshlrev_b32_e32 v68, 12, v18
	v_mov_b32_e32 v69, v1
	v_lshl_add_u64 v[16:17], v[16:17], 0, v[68:69]
	global_load_dwordx4 v[68:71], v[16:17], off
	v_add_u32_e32 v16, 0x420, v31
	v_add_u32_e32 v17, 0x428, v31
	v_add_u32_e32 v18, 0x840, v31
	v_add_u32_e32 v20, 0x848, v31
	v_add_u32_e32 v33, 0xc60, v31
	v_add_u32_e32 v65, 0xc68, v31
	v_add_u32_e32 v72, 0x1080, v31
	v_add_u32_e32 v73, 0x1088, v31
	v_add_u32_e32 v74, 0x14a0, v31
	v_add_u32_e32 v75, 0x14a8, v31
	v_add_u32_e32 v76, 0x18c0, v31
	v_add_u32_e32 v77, 0x18c8, v31
	v_add_u32_e32 v78, 0x1ce0, v31
	v_add_u32_e32 v79, 0x1ce8, v31
	s_lshl_b32 s10, s7, 1
	s_waitcnt vmcnt(7)
	ds_write2_b32 v31, v34, v35 offset1:1
	ds_write2_b32 v31, v36, v37 offset0:2 offset1:3
	s_waitcnt vmcnt(6)
	ds_write2_b32 v16, v40, v41 offset1:1
	ds_write2_b32 v17, v42, v43 offset1:1
	s_waitcnt vmcnt(5)
	ds_write2_b32 v18, v44, v45 offset1:1
	ds_write2_b32 v20, v46, v47 offset1:1
	s_waitcnt vmcnt(4)
	ds_write2_b32 v33, v48, v49 offset1:1
	ds_write2_b32 v65, v50, v51 offset1:1
	s_waitcnt vmcnt(3)
	ds_write2_b32 v72, v52, v53 offset1:1
	ds_write2_b32 v73, v54, v55 offset1:1
	s_waitcnt vmcnt(2)
	ds_write2_b32 v74, v56, v57 offset1:1
	ds_write2_b32 v75, v58, v59 offset1:1
	s_waitcnt vmcnt(1)
	ds_write2_b32 v76, v60, v61 offset1:1
	ds_write2_b32 v77, v62, v63 offset1:1
	s_waitcnt vmcnt(0)
	ds_write2_b32 v78, v68, v69 offset1:1
	ds_write2_b32 v79, v70, v71 offset1:1
	s_waitcnt lgkmcnt(0)
	ds_read2_b32 v[16:17], v29 offset1:33
	s_waitcnt lgkmcnt(0)
	v_cvt_pk_bf16_f32 v34, v16, v17
	ds_read2_b32 v[16:17], v29 offset0:66 offset1:99
	s_waitcnt lgkmcnt(0)
	v_cvt_pk_bf16_f32 v35, v16, v17
	ds_read2_b32 v[16:17], v29 offset0:132 offset1:165
	v_or_b32_e32 v18, s6, v9
	s_waitcnt lgkmcnt(0)
	v_cvt_pk_bf16_f32 v36, v16, v17
	ds_read2_b32 v[16:17], v29 offset0:198 offset1:231
	v_mov_b32_e32 v41, v1
	v_lshlrev_b32_e32 v40, 11, v18
	v_lshl_add_u64 v[42:43], v[4:5], 0, s[10:11]
	s_waitcnt lgkmcnt(0)
	v_cvt_pk_bf16_f32 v37, v16, v17
	ds_read2_b32 v[16:17], v29 offset0:8 offset1:41
	v_lshl_add_u64 v[40:41], v[42:43], 0, v[40:41]
	global_store_dwordx4 v[40:41], v[34:37], off
	v_or_b32_e32 v18, s6, v21
	v_mov_b32_e32 v41, v1
	s_waitcnt lgkmcnt(0)
	v_cvt_pk_bf16_f32 v34, v16, v17
	ds_read2_b32 v[16:17], v29 offset0:74 offset1:107
	s_waitcnt lgkmcnt(0)
	v_cvt_pk_bf16_f32 v35, v16, v17
	ds_read2_b32 v[16:17], v29 offset0:140 offset1:173
	s_waitcnt lgkmcnt(0)
	v_cvt_pk_bf16_f32 v36, v16, v17
	ds_read2_b32 v[16:17], v29 offset0:206 offset1:239
	v_lshlrev_b32_e32 v40, 11, v18
	s_waitcnt lgkmcnt(0)
	v_cvt_pk_bf16_f32 v37, v16, v17
	ds_read2_b32 v[16:17], v29 offset0:16 offset1:49
	v_lshl_add_u64 v[40:41], v[42:43], 0, v[40:41]
	global_store_dwordx4 v[40:41], v[34:37], off
	v_or_b32_e32 v18, s6, v22
	v_mov_b32_e32 v41, v1
	s_waitcnt lgkmcnt(0)
	v_cvt_pk_bf16_f32 v34, v16, v17
	ds_read2_b32 v[16:17], v29 offset0:82 offset1:115
	s_waitcnt lgkmcnt(0)
	v_cvt_pk_bf16_f32 v35, v16, v17
	ds_read2_b32 v[16:17], v29 offset0:148 offset1:181
	s_waitcnt lgkmcnt(0)
	v_cvt_pk_bf16_f32 v36, v16, v17
	ds_read2_b32 v[16:17], v29 offset0:214 offset1:247
	v_lshlrev_b32_e32 v40, 11, v18
	s_waitcnt lgkmcnt(0)
	v_cvt_pk_bf16_f32 v37, v16, v17
	ds_read2_b32 v[16:17], v29 offset0:24 offset1:57
	v_lshl_add_u64 v[40:41], v[42:43], 0, v[40:41]
	global_store_dwordx4 v[40:41], v[34:37], off
	v_or_b32_e32 v18, s6, v24
	v_mov_b32_e32 v41, v1
	s_waitcnt lgkmcnt(0)
	v_cvt_pk_bf16_f32 v34, v16, v17
	ds_read2_b32 v[16:17], v29 offset0:90 offset1:123
	s_waitcnt lgkmcnt(0)
	v_cvt_pk_bf16_f32 v35, v16, v17
	ds_read2_b32 v[16:17], v29 offset0:156 offset1:189
	s_waitcnt lgkmcnt(0)
	v_cvt_pk_bf16_f32 v36, v16, v17
	ds_read2_b32 v[16:17], v29 offset0:222 offset1:255
	v_lshlrev_b32_e32 v40, 11, v18
	s_waitcnt lgkmcnt(0)
	v_cvt_pk_bf16_f32 v37, v16, v17
	v_lshl_add_u64 v[16:17], v[42:43], 0, v[40:41]
	global_store_dwordx4 v[16:17], v[34:37], off
	s_waitcnt lgkmcnt(0)

.Lcv1_2601:
	s_cmpk_lg_i32 s36, 0x800
	s_cbranch_scc1 .Lcv1_2603

	s_load_dwordx2 s[36:37], s[44:45], 0x110
	s_and_b32 s7, s26, 0x1ffc0
	s_lshl_b32 s6, s2, 5
	v_or_b32_e32 v18, s7, v9
	s_and_b32 s6, s6, 0x3e0
	v_lshlrev_b32_e32 v34, 12, v18
	v_or_b32_e32 v18, s7, v21
	s_lshl_b32 s10, s6, 2
	v_lshlrev_b32_e32 v36, 12, v18
	v_or_b32_e32 v18, s7, v22
	s_waitcnt lgkmcnt(0)
	s_add_u32 s36, s36, s10
	v_lshlrev_b32_e32 v44, 12, v18
	v_or_b32_e32 v18, s7, v24
	s_addc_u32 s37, s37, 0
	v_lshlrev_b32_e32 v46, 12, v18
	v_or_b32_e32 v18, s7, v25
	v_lshl_add_u64 v[16:17], s[36:37], 0, v[0:1]
	v_lshlrev_b32_e32 v52, 12, v18
	v_or_b32_e32 v18, s7, v26
	v_lshl_add_u64 v[16:17], v[16:17], 0, s[18:19]
	v_mov_b32_e32 v35, v1
	v_mov_b32_e32 v37, v1
	v_mov_b32_e32 v45, v1
	v_mov_b32_e32 v47, v1
	v_mov_b32_e32 v53, v1
	v_lshlrev_b32_e32 v54, 12, v18
	v_mov_b32_e32 v55, v1
	v_lshl_add_u64 v[34:35], v[16:17], 0, v[34:35]
	v_lshl_add_u64 v[40:41], v[16:17], 0, v[36:37]
	v_lshl_add_u64 v[44:45], v[16:17], 0, v[44:45]
	v_lshl_add_u64 v[48:49], v[16:17], 0, v[46:47]
	v_lshl_add_u64 v[52:53], v[16:17], 0, v[52:53]
	v_lshl_add_u64 v[56:57], v[16:17], 0, v[54:55]
	global_load_dwordx4 v[34:37], v[34:35], off
	s_nop 0
	global_load_dwordx4 v[40:43], v[40:41], off
	s_nop 0
	global_load_dwordx4 v[44:47], v[44:45], off
	s_nop 0
	global_load_dwordx4 v[48:51], v[48:49], off
	s_nop 0
	global_load_dwordx4 v[52:55], v[52:53], off
	s_nop 0
	global_load_dwordx4 v[56:59], v[56:57], off
	v_or_b32_e32 v18, s7, v27
	v_lshlrev_b32_e32 v60, 12, v18
	v_mov_b32_e32 v61, v1
	v_lshl_add_u64 v[60:61], v[16:17], 0, v[60:61]
	v_or_b32_e32 v18, s7, v28
	global_load_dwordx4 v[60:63], v[60:61], off
	v_lshlrev_b32_e32 v68, 12, v18
	v_mov_b32_e32 v69, v1
	v_lshl_add_u64 v[16:17], v[16:17], 0, v[68:69]
	global_load_dwordx4 v[68:71], v[16:17], off
	v_add_u32_e32 v16, 0x420, v31
	v_add_u32_e32 v17, 0x428, v31
	v_add_u32_e32 v18, 0x840, v31
	v_add_u32_e32 v20, 0x848, v31
	v_add_u32_e32 v33, 0xc60, v31
	v_add_u32_e32 v65, 0xc68, v31
	v_add_u32_e32 v72, 0x1080, v31
	v_add_u32_e32 v73, 0x1088, v31
	v_add_u32_e32 v74, 0x14a0, v31
	v_add_u32_e32 v75, 0x14a8, v31
	v_add_u32_e32 v76, 0x18c0, v31
	v_add_u32_e32 v77, 0x18c8, v31
	v_add_u32_e32 v78, 0x1ce0, v31
	v_add_u32_e32 v79, 0x1ce8, v31
	s_lshl_b32 s10, s7, 1
	s_waitcnt vmcnt(7)
	ds_write2_b32 v31, v34, v35 offset1:1
	ds_write2_b32 v31, v36, v37 offset0:2 offset1:3
	s_waitcnt vmcnt(6)
	ds_write2_b32 v16, v40, v41 offset1:1
	ds_write2_b32 v17, v42, v43 offset1:1
	s_waitcnt vmcnt(5)
	ds_write2_b32 v18, v44, v45 offset1:1
	ds_write2_b32 v20, v46, v47 offset1:1
	s_waitcnt vmcnt(4)
	ds_write2_b32 v33, v48, v49 offset1:1
	ds_write2_b32 v65, v50, v51 offset1:1
	s_waitcnt vmcnt(3)
	ds_write2_b32 v72, v52, v53 offset1:1
	ds_write2_b32 v73, v54, v55 offset1:1
	s_waitcnt vmcnt(2)
	ds_write2_b32 v74, v56, v57 offset1:1
	ds_write2_b32 v75, v58, v59 offset1:1
	s_waitcnt vmcnt(1)
	ds_write2_b32 v76, v60, v61 offset1:1
	ds_write2_b32 v77, v62, v63 offset1:1
	s_waitcnt vmcnt(0)
	ds_write2_b32 v78, v68, v69 offset1:1
	ds_write2_b32 v79, v70, v71 offset1:1
	s_waitcnt lgkmcnt(0)
	ds_read2_b32 v[16:17], v29 offset1:33
	s_waitcnt lgkmcnt(0)
	v_cvt_pk_bf16_f32 v34, v16, v17
	ds_read2_b32 v[16:17], v29 offset0:66 offset1:99
	s_waitcnt lgkmcnt(0)
	v_cvt_pk_bf16_f32 v35, v16, v17
	ds_read2_b32 v[16:17], v29 offset0:132 offset1:165
	v_or_b32_e32 v18, s6, v9
	s_waitcnt lgkmcnt(0)
	v_cvt_pk_bf16_f32 v36, v16, v17
	ds_read2_b32 v[16:17], v29 offset0:198 offset1:231
	v_mov_b32_e32 v41, v1
	v_lshlrev_b32_e32 v40, 11, v18
	v_lshl_add_u64 v[42:43], v[6:7], 0, s[10:11]
	s_waitcnt lgkmcnt(0)
	v_cvt_pk_bf16_f32 v37, v16, v17
	ds_read2_b32 v[16:17], v29 offset0:8 offset1:41
	v_lshl_add_u64 v[40:41], v[42:43], 0, v[40:41]
	global_store_dwordx4 v[40:41], v[34:37], off
	v_or_b32_e32 v18, s6, v21
	v_mov_b32_e32 v41, v1
	s_waitcnt lgkmcnt(0)
	v_cvt_pk_bf16_f32 v34, v16, v17
	ds_read2_b32 v[16:17], v29 offset0:74 offset1:107
	s_waitcnt lgkmcnt(0)
	v_cvt_pk_bf16_f32 v35, v16, v17
	ds_read2_b32 v[16:17], v29 offset0:140 offset1:173
	s_waitcnt lgkmcnt(0)
	v_cvt_pk_bf16_f32 v36, v16, v17
	ds_read2_b32 v[16:17], v29 offset0:206 offset1:239
	v_lshlrev_b32_e32 v40, 11, v18
	s_waitcnt lgkmcnt(0)
	v_cvt_pk_bf16_f32 v37, v16, v17
	ds_read2_b32 v[16:17], v29 offset0:16 offset1:49
	v_lshl_add_u64 v[40:41], v[42:43], 0, v[40:41]
	global_store_dwordx4 v[40:41], v[34:37], off
	v_or_b32_e32 v18, s6, v22
	v_mov_b32_e32 v41, v1
	s_waitcnt lgkmcnt(0)
	v_cvt_pk_bf16_f32 v34, v16, v17
	ds_read2_b32 v[16:17], v29 offset0:82 offset1:115
	s_waitcnt lgkmcnt(0)
	v_cvt_pk_bf16_f32 v35, v16, v17
	ds_read2_b32 v[16:17], v29 offset0:148 offset1:181
	s_waitcnt lgkmcnt(0)
	v_cvt_pk_bf16_f32 v36, v16, v17
	ds_read2_b32 v[16:17], v29 offset0:214 offset1:247
	v_lshlrev_b32_e32 v40, 11, v18
	s_waitcnt lgkmcnt(0)
	v_cvt_pk_bf16_f32 v37, v16, v17
	ds_read2_b32 v[16:17], v29 offset0:24 offset1:57
	v_lshl_add_u64 v[40:41], v[42:43], 0, v[40:41]
	global_store_dwordx4 v[40:41], v[34:37], off
	v_or_b32_e32 v18, s6, v24
	v_mov_b32_e32 v41, v1
	s_waitcnt lgkmcnt(0)
	v_cvt_pk_bf16_f32 v34, v16, v17
	ds_read2_b32 v[16:17], v29 offset0:90 offset1:123
	s_waitcnt lgkmcnt(0)
	v_cvt_pk_bf16_f32 v35, v16, v17
	ds_read2_b32 v[16:17], v29 offset0:156 offset1:189
	s_waitcnt lgkmcnt(0)
	v_cvt_pk_bf16_f32 v36, v16, v17
	ds_read2_b32 v[16:17], v29 offset0:222 offset1:255
	v_lshlrev_b32_e32 v40, 11, v18
	s_waitcnt lgkmcnt(0)
	v_cvt_pk_bf16_f32 v37, v16, v17
	v_lshl_add_u64 v[16:17], v[42:43], 0, v[40:41]
	global_store_dwordx4 v[16:17], v[34:37], off
	s_waitcnt lgkmcnt(0)
.Lcv1_2603:
	s_add_i32 s36, s2, 0xfffff400
	v_cndmask_b32_e64 v16, 0, 1, s[16:17]
	s_cmpk_gt_u32 s36, 0x57f
	v_cmp_ne_u32_e64 s[6:7], 1, v16
	s_cbranch_scc1 .Lcv1_2621

	s_and_b32 s37, s36, 0xffff
	s_mul_i32 s37, s37, 0xba2f
	s_lshr_b32 s10, s37, 16
	s_and_b32 s10, s10, 0xffc0
	v_or_b32_e32 v33, s10, v9
	v_mov_b32_e32 v18, 1.0
	s_and_b64 vcc, exec, s[6:7]
	v_mov_b32_e32 v20, 1.0
	s_cbranch_vccnz .Lcv1_2606

	v_lshlrev_b32_e32 v16, 2, v33
	global_load_dword v20, v16, s[14:15]
.Lcv1_2606:
	s_load_dwordx2 s[48:49], s[44:45], 0x128
	s_lshr_b32 s37, s37, 22
	s_mulk_i32 s37, 0x58
	s_sub_i32 s36, s36, s37
	s_lshl_b32 s37, s36, 7
	s_and_b32 s37, s37, 0x3ff80
	s_waitcnt lgkmcnt(0)
	s_add_u32 s48, s48, s37
	s_addc_u32 s49, s49, 0
	v_lshl_add_u64 v[16:17], s[48:49], 0, v[0:1]
	v_lshl_add_u64 v[16:17], v[16:17], 0, s[22:23]
	v_mad_u64_u32 v[34:35], s[48:49], v33, s34, v[16:17]
	global_load_dwordx4 v[34:37], v[34:35], off
	s_and_b64 vcc, exec, s[6:7]
	s_waitcnt vmcnt(0)
	v_pk_mul_f32 v[36:37], v[36:37], v[20:21] op_sel_hi:[1,0]
	v_pk_mul_f32 v[34:35], v[34:35], v[20:21] op_sel_hi:[1,0]
	v_or_b32_e32 v20, s10, v21
	ds_write2_b32 v31, v34, v35 offset1:1
	ds_write2_b32 v31, v36, v37 offset0:2 offset1:3
	s_cbranch_vccnz .Lcv1_2608

	v_lshlrev_b32_e32 v18, 2, v20
	global_load_dword v18, v18, s[14:15]
.Lcv1_2608:
	v_mad_u64_u32 v[34:35], s[48:49], v20, s34, v[16:17]
	global_load_dwordx4 v[34:37], v[34:35], off
	v_or_b32_e32 v33, s10, v22
	v_mov_b32_e32 v20, 1.0
	s_and_b64 vcc, exec, s[6:7]
	s_waitcnt vmcnt(0)
	v_pk_mul_f32 v[36:37], v[36:37], v[18:19] op_sel_hi:[1,0]
	v_pk_mul_f32 v[34:35], v[34:35], v[18:19] op_sel_hi:[1,0]
	v_mov_b32_e32 v18, 1.0
	ds_write2_b32 v32, v34, v35 offset1:1
	ds_write2_b32 v32, v36, v37 offset0:2 offset1:3
	s_cbranch_vccnz .Lcv1_2610

	v_lshlrev_b32_e32 v18, 2, v33
	global_load_dword v18, v18, s[14:15]
.Lcv1_2610:
	v_mad_u64_u32 v[34:35], s[48:49], v33, s34, v[16:17]
	global_load_dwordx4 v[34:37], v[34:35], off
	v_add_u32_e32 v33, v19, v23
	s_and_b64 vcc, exec, s[6:7]
	s_waitcnt vmcnt(0)
	v_pk_mul_f32 v[36:37], v[36:37], v[18:19] op_sel_hi:[1,0]
	v_pk_mul_f32 v[34:35], v[34:35], v[18:19] op_sel_hi:[1,0]
	v_or_b32_e32 v18, s10, v24
	ds_write2_b32 v33, v34, v35 offset1:1
	ds_write2_b32 v33, v36, v37 offset0:2 offset1:3
	s_cbranch_vccnz .Lcv1_2612

	v_lshlrev_b32_e32 v20, 2, v18
	global_load_dword v20, v20, s[14:15]
.Lcv1_2612:
	v_mad_u64_u32 v[34:35], s[48:49], v18, s34, v[16:17]
	global_load_dwordx4 v[40:43], v[34:35], off
	v_add_u32_e32 v35, 0x420, v33
	v_or_b32_e32 v34, s10, v25
	v_mov_b32_e32 v18, 1.0
	s_and_b64 vcc, exec, s[6:7]
	v_add_u32_e32 v44, 0x428, v33
	s_waitcnt vmcnt(0)
	v_pk_mul_f32 v[36:37], v[42:43], v[20:21] op_sel_hi:[1,0]
	v_pk_mul_f32 v[40:41], v[40:41], v[20:21] op_sel_hi:[1,0]
	v_mov_b32_e32 v20, 1.0
	ds_write2_b32 v35, v40, v41 offset1:1
	ds_write2_b32 v44, v36, v37 offset1:1
	s_cbranch_vccnz .Lcv1_2614

	v_lshlrev_b32_e32 v20, 2, v34
	global_load_dword v20, v20, s[14:15]
.Lcv1_2614:
	v_mad_u64_u32 v[34:35], s[48:49], v34, s34, v[16:17]
	global_load_dwordx4 v[34:37], v[34:35], off
	v_add_u32_e32 v40, 0x840, v33
	s_and_b64 vcc, exec, s[6:7]
	v_add_u32_e32 v41, 0x848, v33
	s_waitcnt vmcnt(0)
	v_pk_mul_f32 v[36:37], v[36:37], v[20:21] op_sel_hi:[1,0]
	v_pk_mul_f32 v[34:35], v[34:35], v[20:21] op_sel_hi:[1,0]
	v_or_b32_e32 v20, s10, v26
	ds_write2_b32 v40, v34, v35 offset1:1
	ds_write2_b32 v41, v36, v37 offset1:1
	s_cbranch_vccnz .Lcv1_2616

	v_lshlrev_b32_e32 v18, 2, v20
	global_load_dword v18, v18, s[14:15]
.Lcv1_2616:
	v_mad_u64_u32 v[34:35], s[48:49], v20, s34, v[16:17]
	global_load_dwordx4 v[40:43], v[34:35], off
	v_add_u32_e32 v35, 0xc60, v33
	v_or_b32_e32 v34, s10, v27
	v_mov_b32_e32 v20, 1.0
	s_and_b64 vcc, exec, s[6:7]
	v_add_u32_e32 v44, 0xc68, v33
	s_waitcnt vmcnt(0)
	v_pk_mul_f32 v[36:37], v[42:43], v[18:19] op_sel_hi:[1,0]
	v_pk_mul_f32 v[40:41], v[40:41], v[18:19] op_sel_hi:[1,0]
	v_mov_b32_e32 v18, 1.0
	ds_write2_b32 v35, v40, v41 offset1:1
	ds_write2_b32 v44, v36, v37 offset1:1
	s_cbranch_vccnz .Lcv1_2618

	v_lshlrev_b32_e32 v18, 2, v34
	global_load_dword v18, v18, s[14:15]
.Lcv1_2618:
	v_mad_u64_u32 v[34:35], s[48:49], v34, s34, v[16:17]
	global_load_dwordx4 v[34:37], v[34:35], off
	v_add_u32_e32 v40, 0x1080, v33
	s_and_b64 vcc, exec, s[6:7]
	v_add_u32_e32 v41, 0x1088, v33
	s_waitcnt vmcnt(0)
	v_pk_mul_f32 v[36:37], v[36:37], v[18:19] op_sel_hi:[1,0]
	v_pk_mul_f32 v[34:35], v[34:35], v[18:19] op_sel_hi:[1,0]
	v_or_b32_e32 v18, s10, v28
	ds_write2_b32 v40, v34, v35 offset1:1
	ds_write2_b32 v41, v36, v37 offset1:1
	s_cbranch_vccnz .Lcv1_2620

	v_lshlrev_b32_e32 v20, 2, v18
	global_load_dword v20, v20, s[14:15]

.Lcv1_2621:
	s_add_i32 s36, s2, 0xffffee80
	s_cmpk_gt_u32 s36, 0x57f
	s_cbranch_scc1 .Lcv1_2639

	s_and_b32 s37, s36, 0xffff
	s_mul_i32 s37, s37, 0xba2f
	s_lshr_b32 s10, s37, 16
	s_and_b32 s10, s10, 0xffc0
	v_or_b32_e32 v33, s10, v9
	v_mov_b32_e32 v18, 1.0
	s_and_b64 vcc, exec, s[6:7]
	v_mov_b32_e32 v20, 1.0
	s_cbranch_vccnz .Lcv1_2624

	v_lshlrev_b32_e32 v16, 2, v33
	global_load_dword v20, v16, s[14:15]
.Lcv1_2624:
	s_load_dwordx2 s[48:49], s[44:45], 0x130
	s_lshr_b32 s37, s37, 22
	s_mulk_i32 s37, 0x58
	s_sub_i32 s36, s36, s37
	s_lshl_b32 s37, s36, 7
	s_and_b32 s37, s37, 0x3ff80
	s_waitcnt lgkmcnt(0)
	s_add_u32 s48, s48, s37
	s_addc_u32 s49, s49, 0
	v_lshl_add_u64 v[16:17], s[48:49], 0, v[0:1]
	v_lshl_add_u64 v[16:17], v[16:17], 0, s[22:23]
	v_mad_u64_u32 v[34:35], s[48:49], v33, s34, v[16:17]
	global_load_dwordx4 v[34:37], v[34:35], off
	s_and_b64 vcc, exec, s[6:7]
	s_waitcnt vmcnt(0)
	v_pk_mul_f32 v[36:37], v[36:37], v[20:21] op_sel_hi:[1,0]
	v_pk_mul_f32 v[34:35], v[34:35], v[20:21] op_sel_hi:[1,0]
	v_or_b32_e32 v20, s10, v21
	ds_write2_b32 v31, v34, v35 offset1:1
	ds_write2_b32 v31, v36, v37 offset0:2 offset1:3
	s_cbranch_vccnz .Lcv1_2626

	v_lshlrev_b32_e32 v18, 2, v20
	global_load_dword v18, v18, s[14:15]

.Lcv1_2639:
	s_add_i32 s6, s2, 0xffffe900
	s_cmpk_gt_u32 s6, 0x57f
	v_add_u32_e32 v16, 0x420, v31
	v_add_u32_e32 v17, 0x428, v31
	v_add_u32_e32 v18, 0x840, v31
	v_add_u32_e32 v20, 0x848, v31
	v_add_u32_e32 v33, 0xc60, v31
	v_add_u32_e32 v34, 0xc68, v31
	v_add_u32_e32 v35, 0x1080, v31
	v_add_u32_e32 v36, 0x1088, v31
	v_add_u32_e32 v37, 0x14a0, v31
	v_add_u32_e32 v40, 0x14a8, v31
	v_add_u32_e32 v41, 0x18c0, v31
	v_add_u32_e32 v42, 0x18c8, v31
	v_add_u32_e32 v43, 0x1ce0, v31
	v_add_u32_e32 v44, 0x1ce8, v31
	s_cbranch_scc1 .Lcv1_2641

	s_load_dwordx2 s[36:37], s[44:45], 0x138
	s_add_i32 s6, s26, 0xfffde200
	s_and_b32 s7, s6, 0xfc0
	s_lshl_b32 s6, s2, 5
	s_and_b32 s6, s6, 0x3e0
	s_lshl_b32 s10, s6, 2
	s_waitcnt lgkmcnt(0)
	s_add_u32 s36, s36, s10
	s_addc_u32 s37, s37, 0
	v_lshl_add_u64 v[46:47], s[36:37], 0, v[0:1]
	v_or_b32_e32 v45, s7, v9
	v_lshl_add_u64 v[62:63], v[46:47], 0, s[22:23]
	v_lshlrev_b32_e32 v46, 12, v45
	v_or_b32_e32 v45, s7, v21
	v_lshlrev_b32_e32 v48, 12, v45
	v_or_b32_e32 v45, s7, v22
	v_lshlrev_b32_e32 v54, 12, v45
	v_or_b32_e32 v45, s7, v24
	v_lshlrev_b32_e32 v56, 12, v45
	v_or_b32_e32 v45, s7, v25
	v_lshlrev_b32_e32 v68, 12, v45
	v_or_b32_e32 v45, s7, v26
	v_mov_b32_e32 v47, v1
	v_mov_b32_e32 v49, v1
	v_mov_b32_e32 v55, v1
	v_mov_b32_e32 v57, v1
	v_mov_b32_e32 v69, v1
	v_lshlrev_b32_e32 v70, 12, v45
	v_mov_b32_e32 v71, v1
	v_lshl_add_u64 v[46:47], v[62:63], 0, v[46:47]
	v_lshl_add_u64 v[50:51], v[62:63], 0, v[48:49]
	v_lshl_add_u64 v[54:55], v[62:63], 0, v[54:55]
	v_lshl_add_u64 v[58:59], v[62:63], 0, v[56:57]
	v_lshl_add_u64 v[68:69], v[62:63], 0, v[68:69]
	v_lshl_add_u64 v[72:73], v[62:63], 0, v[70:71]
	global_load_dwordx4 v[46:49], v[46:47], off
	s_nop 0
	global_load_dwordx4 v[50:53], v[50:51], off
	s_nop 0
	global_load_dwordx4 v[54:57], v[54:55], off
	s_nop 0
	global_load_dwordx4 v[58:61], v[58:59], off
	s_nop 0
	global_load_dwordx4 v[68:71], v[68:69], off
	s_nop 0
	global_load_dwordx4 v[72:75], v[72:73], off
	v_or_b32_e32 v45, s7, v27
	v_lshlrev_b32_e32 v76, 12, v45
	v_mov_b32_e32 v77, v1
	v_lshl_add_u64 v[76:77], v[62:63], 0, v[76:77]
	v_or_b32_e32 v45, s7, v28
	global_load_dwordx4 v[76:79], v[76:77], off
	v_lshlrev_b32_e32 v80, 12, v45
	v_mov_b32_e32 v81, v1
	v_lshl_add_u64 v[62:63], v[62:63], 0, v[80:81]
	global_load_dwordx4 v[80:83], v[62:63], off
	v_or_b32_e32 v45, s6, v9
	s_lshl_b32 s10, s7, 1
	s_waitcnt vmcnt(7)
	ds_write2_b32 v31, v46, v47 offset1:1
	ds_write2_b32 v31, v48, v49 offset0:2 offset1:3
	s_waitcnt vmcnt(6)
	ds_write2_b32 v16, v50, v51 offset1:1
	ds_write2_b32 v17, v52, v53 offset1:1
	s_waitcnt vmcnt(5)
	ds_write2_b32 v18, v54, v55 offset1:1
	ds_write2_b32 v20, v56, v57 offset1:1
	s_waitcnt vmcnt(4)
	ds_write2_b32 v33, v58, v59 offset1:1
	ds_write2_b32 v34, v60, v61 offset1:1
	s_waitcnt vmcnt(3)
	ds_write2_b32 v35, v68, v69 offset1:1
	ds_write2_b32 v36, v70, v71 offset1:1
	s_waitcnt vmcnt(2)
	ds_write2_b32 v37, v72, v73 offset1:1
	ds_write2_b32 v40, v74, v75 offset1:1
	s_waitcnt vmcnt(1)
	ds_write2_b32 v41, v76, v77 offset1:1
	ds_write2_b32 v42, v78, v79 offset1:1
	s_waitcnt vmcnt(0)
	ds_write2_b32 v43, v80, v81 offset1:1
	ds_write2_b32 v44, v82, v83 offset1:1
	s_waitcnt lgkmcnt(0)
	ds_read2_b32 v[46:47], v29 offset1:33
	s_waitcnt lgkmcnt(0)
	v_cvt_pk_bf16_f32 v46, v46, v47
	ds_read2_b32 v[48:49], v29 offset0:66 offset1:99
	s_waitcnt lgkmcnt(0)
	v_cvt_pk_bf16_f32 v47, v48, v49
	ds_read2_b32 v[48:49], v29 offset0:132 offset1:165
	v_mov_b32_e32 v53, v1
	v_mul_u32_u24_e32 v52, 0x1600, v45
	v_lshl_add_u64 v[54:55], v[12:13], 0, s[10:11]
	s_waitcnt lgkmcnt(0)
	v_cvt_pk_bf16_f32 v48, v48, v49
	ds_read2_b32 v[50:51], v29 offset0:198 offset1:231
	s_waitcnt lgkmcnt(0)
	v_cvt_pk_bf16_f32 v49, v50, v51
	v_lshl_add_u64 v[52:53], v[54:55], 0, v[52:53]
	ds_read2_b32 v[50:51], v29 offset0:8 offset1:41
	global_store_dwordx4 v[52:53], v[46:49], off
	v_or_b32_e32 v45, s6, v21
	v_mov_b32_e32 v53, v1
	s_waitcnt lgkmcnt(0)
	v_cvt_pk_bf16_f32 v46, v50, v51
	ds_read2_b32 v[48:49], v29 offset0:74 offset1:107
	s_waitcnt lgkmcnt(0)
	v_cvt_pk_bf16_f32 v47, v48, v49
	ds_read2_b32 v[48:49], v29 offset0:140 offset1:173
	v_mul_u32_u24_e32 v52, 0x1600, v45
	s_waitcnt lgkmcnt(0)
	v_cvt_pk_bf16_f32 v48, v48, v49
	ds_read2_b32 v[50:51], v29 offset0:206 offset1:239
	s_waitcnt lgkmcnt(0)
	v_cvt_pk_bf16_f32 v49, v50, v51
	v_lshl_add_u64 v[52:53], v[54:55], 0, v[52:53]
	ds_read2_b32 v[50:51], v29 offset0:16 offset1:49
	global_store_dwordx4 v[52:53], v[46:49], off
	v_or_b32_e32 v45, s6, v22
	v_mov_b32_e32 v53, v1
	s_waitcnt lgkmcnt(0)
	v_cvt_pk_bf16_f32 v46, v50, v51
	ds_read2_b32 v[48:49], v29 offset0:82 offset1:115
	s_waitcnt lgkmcnt(0)
	v_cvt_pk_bf16_f32 v47, v48, v49
	ds_read2_b32 v[48:49], v29 offset0:148 offset1:181
	v_mul_u32_u24_e32 v52, 0x1600, v45
	s_waitcnt lgkmcnt(0)
	v_cvt_pk_bf16_f32 v48, v48, v49
	ds_read2_b32 v[50:51], v29 offset0:214 offset1:247
	s_waitcnt lgkmcnt(0)
	v_cvt_pk_bf16_f32 v49, v50, v51
	v_lshl_add_u64 v[52:53], v[54:55], 0, v[52:53]
	ds_read2_b32 v[50:51], v29 offset0:24 offset1:57
	global_store_dwordx4 v[52:53], v[46:49], off
	v_or_b32_e32 v45, s6, v24
	v_mov_b32_e32 v53, v1
	s_waitcnt lgkmcnt(0)
	v_cvt_pk_bf16_f32 v46, v50, v51
	ds_read2_b32 v[48:49], v29 offset0:90 offset1:123
	s_waitcnt lgkmcnt(0)
	v_cvt_pk_bf16_f32 v47, v48, v49
	ds_read2_b32 v[48:49], v29 offset0:156 offset1:189
	s_waitcnt lgkmcnt(0)
	v_cvt_pk_bf16_f32 v48, v48, v49
	ds_read2_b32 v[50:51], v29 offset0:222 offset1:255
	v_mul_u32_u24_e32 v52, 0x1600, v45
	s_waitcnt lgkmcnt(0)
	v_cvt_pk_bf16_f32 v49, v50, v51
	v_lshl_add_u64 v[50:51], v[54:55], 0, v[52:53]
	global_store_dwordx4 v[50:51], v[46:49], off
	s_waitcnt lgkmcnt(0)
.Lcv1_2641:
	s_and_b32 s6, s2, 0xffffffe0
	s_cmpk_lg_i32 s6, 0x1c80
	s_cbranch_scc1 .Lcv1_2577

	s_load_dwordx2 s[36:37], s[44:45], 0x78
	s_lshl_b32 s6, s2, 5
	s_and_b32 s6, s6, 0xe0
	s_and_b32 s7, s28, 0xc0
	s_lshl_b32 s10, s6, 2
	s_waitcnt lgkmcnt(0)
	s_add_u32 s36, s36, s10
	s_addc_u32 s37, s37, 0
	v_lshl_add_u64 v[46:47], s[36:37], 0, v[0:1]
	v_or_b32_e32 v45, s7, v9
	v_lshl_add_u64 v[62:63], v[46:47], 0, s[24:25]
	v_lshlrev_b32_e32 v46, 10, v45
	v_or_b32_e32 v45, s7, v21
	v_lshlrev_b32_e32 v48, 10, v45
	v_or_b32_e32 v45, s7, v22
	v_lshlrev_b32_e32 v54, 10, v45
	v_or_b32_e32 v45, s7, v24
	v_lshlrev_b32_e32 v56, 10, v45
	v_or_b32_e32 v45, s7, v25
	v_lshlrev_b32_e32 v68, 10, v45
	v_or_b32_e32 v45, s7, v26
	v_mov_b32_e32 v47, v1
	v_mov_b32_e32 v49, v1
	v_mov_b32_e32 v55, v1
	v_mov_b32_e32 v57, v1
	v_mov_b32_e32 v69, v1
	v_lshlrev_b32_e32 v70, 10, v45
	v_mov_b32_e32 v71, v1
	v_lshl_add_u64 v[46:47], v[62:63], 0, v[46:47]
	v_lshl_add_u64 v[50:51], v[62:63], 0, v[48:49]
	v_lshl_add_u64 v[54:55], v[62:63], 0, v[54:55]
	v_lshl_add_u64 v[58:59], v[62:63], 0, v[56:57]
	v_lshl_add_u64 v[68:69], v[62:63], 0, v[68:69]
	v_lshl_add_u64 v[72:73], v[62:63], 0, v[70:71]
	global_load_dwordx4 v[46:49], v[46:47], off
	s_nop 0
	global_load_dwordx4 v[50:53], v[50:51], off
	s_nop 0
	global_load_dwordx4 v[54:57], v[54:55], off
	s_nop 0
	global_load_dwordx4 v[58:61], v[58:59], off
	s_nop 0
	global_load_dwordx4 v[68:71], v[68:69], off
	s_nop 0
	global_load_dwordx4 v[72:75], v[72:73], off
	v_or_b32_e32 v45, s7, v27
	v_lshlrev_b32_e32 v76, 10, v45
	v_mov_b32_e32 v77, v1
	v_lshl_add_u64 v[76:77], v[62:63], 0, v[76:77]
	v_or_b32_e32 v45, s7, v28
	global_load_dwordx4 v[76:79], v[76:77], off
	v_lshlrev_b32_e32 v80, 10, v45
	v_mov_b32_e32 v81, v1
	v_lshl_add_u64 v[62:63], v[62:63], 0, v[80:81]
	global_load_dwordx4 v[80:83], v[62:63], off
	s_lshl_b32 s10, s7, 1
	s_waitcnt vmcnt(7)
	ds_write2_b32 v31, v46, v47 offset1:1
	ds_write2_b32 v31, v48, v49 offset0:2 offset1:3
	s_waitcnt vmcnt(6)
	ds_write2_b32 v16, v50, v51 offset1:1
	ds_write2_b32 v17, v52, v53 offset1:1
	s_waitcnt vmcnt(5)
	ds_write2_b32 v18, v54, v55 offset1:1
	ds_write2_b32 v20, v56, v57 offset1:1
	s_waitcnt vmcnt(4)
	ds_write2_b32 v33, v58, v59 offset1:1
	ds_write2_b32 v34, v60, v61 offset1:1
	s_waitcnt vmcnt(3)
	ds_write2_b32 v35, v68, v69 offset1:1
	ds_write2_b32 v36, v70, v71 offset1:1
	s_waitcnt vmcnt(2)
	ds_write2_b32 v37, v72, v73 offset1:1
	ds_write2_b32 v40, v74, v75 offset1:1
	s_waitcnt vmcnt(1)
	ds_write2_b32 v41, v76, v77 offset1:1
	ds_write2_b32 v42, v78, v79 offset1:1
	s_waitcnt vmcnt(0)
	ds_write2_b32 v43, v80, v81 offset1:1
	ds_write2_b32 v44, v82, v83 offset1:1
	s_waitcnt lgkmcnt(0)
	ds_read2_b32 v[16:17], v29 offset1:33
	s_waitcnt lgkmcnt(0)
	v_cvt_pk_bf16_f32 v34, v16, v17
	ds_read2_b32 v[16:17], v29 offset0:66 offset1:99
	s_waitcnt lgkmcnt(0)
	v_cvt_pk_bf16_f32 v35, v16, v17
	ds_read2_b32 v[16:17], v29 offset0:132 offset1:165
	v_or_b32_e32 v18, s6, v9
	s_waitcnt lgkmcnt(0)
	v_cvt_pk_bf16_f32 v36, v16, v17
	ds_read2_b32 v[16:17], v29 offset0:198 offset1:231
	v_mov_b32_e32 v41, v1
	v_lshlrev_b32_e32 v40, 9, v18
	v_lshl_add_u64 v[42:43], v[14:15], 0, s[10:11]
	s_waitcnt lgkmcnt(0)
	v_cvt_pk_bf16_f32 v37, v16, v17
	ds_read2_b32 v[16:17], v29 offset0:8 offset1:41
	v_lshl_add_u64 v[40:41], v[42:43], 0, v[40:41]
	global_store_dwordx4 v[40:41], v[34:37], off
	v_or_b32_e32 v18, s6, v21
	v_mov_b32_e32 v41, v1
	s_waitcnt lgkmcnt(0)
	v_cvt_pk_bf16_f32 v34, v16, v17
	ds_read2_b32 v[16:17], v29 offset0:74 offset1:107
	s_waitcnt lgkmcnt(0)
	v_cvt_pk_bf16_f32 v35, v16, v17
	ds_read2_b32 v[16:17], v29 offset0:140 offset1:173
	s_waitcnt lgkmcnt(0)
	v_cvt_pk_bf16_f32 v36, v16, v17
	ds_read2_b32 v[16:17], v29 offset0:206 offset1:239
	v_lshlrev_b32_e32 v40, 9, v18
	s_waitcnt lgkmcnt(0)
	v_cvt_pk_bf16_f32 v37, v16, v17
	ds_read2_b32 v[16:17], v29 offset0:16 offset1:49
	v_lshl_add_u64 v[40:41], v[42:43], 0, v[40:41]
	global_store_dwordx4 v[40:41], v[34:37], off
	v_or_b32_e32 v18, s6, v22
	v_mov_b32_e32 v41, v1
	s_waitcnt lgkmcnt(0)
	v_cvt_pk_bf16_f32 v34, v16, v17
	ds_read2_b32 v[16:17], v29 offset0:82 offset1:115
	s_waitcnt lgkmcnt(0)
	v_cvt_pk_bf16_f32 v35, v16, v17
	ds_read2_b32 v[16:17], v29 offset0:148 offset1:181
	s_waitcnt lgkmcnt(0)
	v_cvt_pk_bf16_f32 v36, v16, v17
	ds_read2_b32 v[16:17], v29 offset0:214 offset1:247
	v_lshlrev_b32_e32 v40, 9, v18
	s_waitcnt lgkmcnt(0)
	v_cvt_pk_bf16_f32 v37, v16, v17
	ds_read2_b32 v[16:17], v29 offset0:24 offset1:57
	v_lshl_add_u64 v[40:41], v[42:43], 0, v[40:41]
	global_store_dwordx4 v[40:41], v[34:37], off
	v_or_b32_e32 v18, s6, v24
	v_mov_b32_e32 v41, v1
	s_waitcnt lgkmcnt(0)
	v_cvt_pk_bf16_f32 v34, v16, v17
	ds_read2_b32 v[16:17], v29 offset0:90 offset1:123
	s_waitcnt lgkmcnt(0)
	v_cvt_pk_bf16_f32 v35, v16, v17
	ds_read2_b32 v[16:17], v29 offset0:156 offset1:189
	s_waitcnt lgkmcnt(0)
	v_cvt_pk_bf16_f32 v36, v16, v17
	ds_read2_b32 v[16:17], v29 offset0:222 offset1:255
	v_lshlrev_b32_e32 v40, 9, v18
	s_waitcnt lgkmcnt(0)
	v_cvt_pk_bf16_f32 v37, v16, v17
	v_lshl_add_u64 v[16:17], v[42:43], 0, v[40:41]
	global_store_dwordx4 v[16:17], v[34:37], off
	s_waitcnt lgkmcnt(0)
	s_branch .Lcv1_2577
.Lcv1_2643:
.Lcv1_skip:
.LBB0_2144:
	s_cmp_lt_i32 s43, 17
	s_cbranch_scc1 .LBB0_2198
	s_waitcnt vmcnt(0)
	s_barrier
	s_and_saveexec_b64 s[4:5], s[86:87]
	s_cbranch_execz .LBB0_2197
	s_add_i32 s1, 0, 0x23fc0
	v_mov_b32_e32 v0, s1
	s_waitcnt vmcnt(0) expcnt(0) lgkmcnt(0)
	ds_read_b32 v2, v0
	s_add_i32 s1, 0, 0x23fc4
	v_mov_b32_e32 v0, s1
	ds_read_b32 v0, v0
	s_waitcnt lgkmcnt(1)
	v_cmp_ne_u32_e32 vcc, 0, v2
	s_cbranch_vccnz .LBB0_2161
	s_add_u32 s6, s40, 0x1000
	s_load_dwordx2 s[2:3], s[10:11], 0x4
	s_addc_u32 s7, s41, 0
	s_add_u32 s8, s40, 0x1100
	s_addc_u32 s9, s41, 0
	s_add_u32 s10, s40, 0x1200
	s_addc_u32 s11, s41, 0
	s_waitcnt lgkmcnt(0)
	s_mul_i32 s0, s2, s0
	s_add_u32 s12, s40, 0x1300
	s_mul_i32 s0, s0, s3
	s_addc_u32 s13, s41, 0
	s_mov_b32 s1, 1
	v_mov_b32_e32 v16, 0
	s_branch .LBB0_2149

.LBB0_2578:
	s_cmpk_lt_i32 s2, 0xc00
	s_cbranch_scc1 .LBB0_2577
	s_cmpk_gt_u32 s2, 0x7ff
	s_cbranch_scc1 .LBB0_2597
	s_lshr_b32 s6, s2, 1
	s_and_b32 s6, s6, 0x3c0
	v_or_b32_e32 v33, s6, v9
	v_mov_b32_e32 v18, 1.0
	s_and_b64 vcc, exec, s[4:5]
	v_mov_b32_e32 v20, 1.0
	s_cbranch_vccnz .LBB0_2581
	v_lshlrev_b32_e32 v16, 2, v33
	global_load_dword v20, v16, s[12:13]
